# modnorm row loops of the latent rows (P8/P11/P18) hand-written: rows prefetched two ahead in three register sets, modulation loads batched, counted vmcnt waits; plus batched EpiRes epilogues
# speedup vs baseline: 1.0665x; 1.0064x over previous
; #define LANE_IDS() const int f_tid = tid_(); const int f_lane = f_tid & 63; const int f_gtid = blockIdx.x * (NWAVES * 64) + f_tid; (void)f_lane; (void)f_gtid
;     LANE_IDS();
;     if (F.gw >= wave0) for (int row = row_begin + (F.gw - wave0); row < nrows; row += F.NGW - wave0) {
;         const bool isctx = row >= NLAT; const int b = isctx ? 8 : (row >> 12);
;         const size_t roff = isctx ? (size_t)(row - NLAT) * DM : (size_t)row * DM; const void* sp = isctx ? src_ctx : src_lat;
;         f32x4 v[4]; float ss = 0.f;
;         if (SB) { const u32x2* xr = (const u32x2*)((const bf16*)sp + roff) + f_lane;
; #pragma unroll
;             for (int j = 0; j < 4; ++j) { const u32x2 r = xr[64 * j]; v[j] = (f32x4){__uint_as_float(r.x << 16), __uint_as_float(r.x & 0xffff0000u), __uint_as_float(r.y << 16), __uint_as_float(r.y & 0xffff0000u)}; } }
;         else { const f32x4* xr = (const f32x4*)((const float*)sp + roff) + f_lane;
; #pragma unroll
;             for (int j = 0; j < 4; ++j) v[j] = xr[64 * j]; }
;         if (part != nullptr && isctx) {
;             const f32x4* p0 = (const f32x4*)(part + (size_t)(row - NLAT) * DM) + f_lane; const f32x4* p1 = p0 + (size_t)NCTX * DM / 4; const f32x4* g4p = (const f32x4*)pgate + f_lane;
; #pragma unroll
;             for (int j = 0; j < 4; ++j) v[j] += g4p[64 * j] * (p0[64 * j] + p1[64 * j]); }
; #pragma unroll
;         for (int j = 0; j < 4; ++j) ss += (v[j].x * v[j].x + v[j].y * v[j].y) + (v[j].z * v[j].z + v[j].w * v[j].w);
;         const float rstd = rsqrtf(wave_sum(ss) * (1.0f / DM) + EPS);
.LBB0_769:
	s_add_u32 s3, s54, 0x1000
	s_addc_u32 s33, s55, 0
	s_mov_b64 s[26:27], s[86:87]
	s_add_u32 s86, s54, 0xe800000
	s_mov_b64 s[22:23], s[80:81]
	s_addc_u32 s87, s55, 0
	s_andn2_b64 vcc, exec, s[4:5]
	s_cbranch_vccnz .LBB0_773
	s_lshl_b32 s12, s84, 3
	s_cmp_lt_i32 s46, s12
	s_cselect_b64 s[8:9], -1, 0
	s_sub_i32 s4, s46, s12
	s_cmpk_gt_i32 s4, 0x7fff
	s_cselect_b64 s[10:11], -1, 0
	s_or_b64 s[8:9], s[8:9], s[10:11]
	s_mov_b64 s[6:7], s[0:1]
	v_mov_b32_e32 v0, v188
	s_and_b64 vcc, exec, s[8:9]
	s_cbranch_vccnz .LBB0_773
	v_and_b32_e32 v16, 63, v0
	v_mbcnt_lo_u32_b32 v0, -1, 0
	v_mbcnt_hi_u32_b32 v0, -1, v0
	v_and_b32_e32 v2, 64, v0
	v_add_u32_e32 v2, 64, v2
	v_xor_b32_e32 v3, 1, v0
	v_cmp_lt_i32_e32 vcc, v3, v2
	s_load_dwordx2 s[6:7], s[6:7], 0x38
	v_mov_b32_e32 v1, 0
	v_cndmask_b32_e32 v3, v0, v3, vcc
	v_lshlrev_b32_e32 v8, 2, v3
	v_xor_b32_e32 v3, 2, v0
	v_cmp_lt_i32_e32 vcc, v3, v2
	v_mov_b32_e32 v14, 0x358637bd
	s_mov_b32 s13, 0x800000
	v_cndmask_b32_e32 v3, v0, v3, vcc
	v_lshlrev_b32_e32 v9, 2, v3
	v_xor_b32_e32 v3, 4, v0
	v_cmp_lt_i32_e32 vcc, v3, v2
	s_mov_b64 s[8:9], 0x4000
	s_movk_i32 s14, 0x4000
	v_cndmask_b32_e32 v3, v0, v3, vcc
	v_lshlrev_b32_e32 v10, 2, v3
	v_xor_b32_e32 v3, 8, v0
	v_cmp_lt_i32_e32 vcc, v3, v2
	s_movk_i32 s15, 0x3000
	v_readlane_b32 s18, v251, 5
	v_cndmask_b32_e32 v3, v0, v3, vcc
	v_lshlrev_b32_e32 v11, 2, v3
	v_xor_b32_e32 v3, 16, v0
	v_cmp_lt_i32_e32 vcc, v3, v2
	v_readlane_b32 s19, v251, 6
	s_nop 0
	v_cndmask_b32_e32 v3, v0, v3, vcc
	v_lshlrev_b32_e32 v12, 2, v3
	v_xor_b32_e32 v3, 32, v0
	v_cmp_lt_i32_e32 vcc, v3, v2
	s_nop 1
	v_cndmask_b32_e32 v0, v0, v3, vcc
	v_lshlrev_b32_e32 v13, 2, v0
	v_lshlrev_b32_e32 v0, 4, v16
	s_waitcnt lgkmcnt(0)
	v_lshl_add_u64 v[2:3], s[6:7], 0, v[0:1]
	v_lshlrev_b32_e32 v0, 3, v16
	v_lshl_add_u64 v[4:5], s[86:87], 0, v[0:1]
	v_lshl_add_u64 v[6:7], s[52:53], 0, v[0:1]
	v_lshlrev_b32_e32 v0, 4, v16
	s_mov_b64 s[6:7], 0x3000
	s_sub_i32 s5, s18, s12
	global_load_dwordx4 v[64:67], v[2:3], off offset:0
	global_load_dwordx4 v[68:71], v[2:3], off offset:1024
	global_load_dwordx4 v[72:75], v[2:3], off offset:2048
	global_load_dwordx4 v[76:79], v[2:3], off offset:3072
	s_mov_b32 s10, s4
	s_lshl_b32 s10, s10, 11
	s_mov_b32 s11, 0
	v_lshl_add_u64 v[156:157], v[6:7], 0, s[10:11]
	global_load_dwordx2 v[80:81], v[156:157], off offset:0
	global_load_dwordx2 v[82:83], v[156:157], off offset:512
	global_load_dwordx2 v[84:85], v[156:157], off offset:1024
	global_load_dwordx2 v[86:87], v[156:157], off offset:1536
	s_add_i32 s10, s4, s5
	s_min_i32 s10, s10, 0x7fff
	s_lshl_b32 s10, s10, 11
	s_mov_b32 s11, 0
	v_lshl_add_u64 v[156:157], v[6:7], 0, s[10:11]
	global_load_dwordx2 v[88:89], v[156:157], off offset:0
	global_load_dwordx2 v[90:91], v[156:157], off offset:512
	global_load_dwordx2 v[92:93], v[156:157], off offset:1024
	global_load_dwordx2 v[94:95], v[156:157], off offset:1536
	s_waitcnt vmcnt(4)
.Lmn_p8_c0:
	s_ashr_i32 s16, s4, 12
	s_mul_i32 s16, s16, 0x6000
	s_add_u32 s16, s3, s16
	s_addc_u32 s17, s33, 0
	s_add_u32 s100, s16, 0x4000
	s_addc_u32 s101, s17, 0
	v_lshl_add_u64 v[162:163], s[100:101], 0, v[0:1]
	global_load_dwordx4 v[104:107], v[162:163], off offset:0
	global_load_dwordx4 v[108:111], v[162:163], off offset:1024
	global_load_dwordx4 v[112:115], v[162:163], off offset:2048
	global_load_dwordx4 v[116:119], v[162:163], off offset:3072
	s_add_u32 s100, s16, 0x3000
	s_addc_u32 s101, s17, 0
	v_lshl_add_u64 v[164:165], s[100:101], 0, v[0:1]
	global_load_dwordx4 v[120:123], v[164:165], off offset:0
	global_load_dwordx4 v[124:127], v[164:165], off offset:1024
	global_load_dwordx4 v[128:131], v[164:165], off offset:2048
	global_load_dwordx4 v[132:135], v[164:165], off offset:3072
	s_lshl_b32 s10, s5, 1
	s_add_i32 s10, s10, s4
	s_min_i32 s10, s10, 0x7fff
	s_lshl_b32 s10, s10, 11
	s_mov_b32 s11, 0
	v_lshl_add_u64 v[156:157], v[6:7], 0, s[10:11]
	global_load_dwordx2 v[96:97], v[156:157], off offset:0
	global_load_dwordx2 v[98:99], v[156:157], off offset:512
	global_load_dwordx2 v[100:101], v[156:157], off offset:1024
	global_load_dwordx2 v[102:103], v[156:157], off offset:1536
	s_waitcnt vmcnt(20)
	v_lshlrev_b32_e32 v136, 16, v80
	v_and_b32_e32 v137, 0xffff0000, v80
	v_lshlrev_b32_e32 v138, 16, v81
	v_and_b32_e32 v139, 0xffff0000, v81
	v_lshlrev_b32_e32 v140, 16, v82
	v_and_b32_e32 v141, 0xffff0000, v82
	v_lshlrev_b32_e32 v142, 16, v83
	v_and_b32_e32 v143, 0xffff0000, v83
	v_lshlrev_b32_e32 v144, 16, v84
	v_and_b32_e32 v145, 0xffff0000, v84
	v_lshlrev_b32_e32 v146, 16, v85
	v_and_b32_e32 v147, 0xffff0000, v85
	v_lshlrev_b32_e32 v148, 16, v86
	v_and_b32_e32 v149, 0xffff0000, v86
	v_lshlrev_b32_e32 v150, 16, v87
	v_and_b32_e32 v151, 0xffff0000, v87
	v_mul_f32_e32 v152, v136, v136
	v_mul_f32_e32 v153, v137, v137
	v_fmac_f32_e32 v152, v138, v138
	v_fmac_f32_e32 v153, v139, v139
	v_fmac_f32_e32 v152, v140, v140
	v_fmac_f32_e32 v153, v141, v141
	v_fmac_f32_e32 v152, v142, v142
	v_fmac_f32_e32 v153, v143, v143
	v_fmac_f32_e32 v152, v144, v144
	v_fmac_f32_e32 v153, v145, v145
	v_fmac_f32_e32 v152, v146, v146
	v_fmac_f32_e32 v153, v147, v147
	v_fmac_f32_e32 v152, v148, v148
	v_fmac_f32_e32 v153, v149, v149
	v_fmac_f32_e32 v152, v150, v150
	v_fmac_f32_e32 v153, v151, v151
	v_add_f32_e32 v152, v152, v153
	ds_bpermute_b32 v153, v8, v152
	s_waitcnt lgkmcnt(0)
	v_add_f32_e32 v152, v152, v153
	ds_bpermute_b32 v153, v9, v152
	s_waitcnt lgkmcnt(0)
	v_add_f32_e32 v152, v152, v153
	ds_bpermute_b32 v153, v10, v152
	s_waitcnt lgkmcnt(0)
	v_add_f32_e32 v152, v152, v153
	ds_bpermute_b32 v153, v11, v152
	s_waitcnt lgkmcnt(0)
	v_add_f32_e32 v152, v152, v153
	ds_bpermute_b32 v153, v12, v152
	s_waitcnt lgkmcnt(0)
; __device__ __forceinline__ unsigned cvt_pk_bf16(float lo, float hi) { unsigned r; asm volatile("v_cvt_pk_bf16_f32 %0, %1, %2" : "=v"(r) : "v"(lo), "v"(hi)); return r; }
;     ...
;         for (int j = 0; j < 4; ++j) ss += (v[j].x * v[j].x + v[j].y * v[j].y) + (v[j].z * v[j].z + v[j].w * v[j].w);
;         const float rstd = rsqrtf(wave_sum(ss) * (1.0f / DM) + EPS);
;         const f32x4* g4 = (const f32x4*)gnorm + f_lane; const f32x4* sh4 = (const f32x4*)(modl + b * MODS + shc * DM) + f_lane; const f32x4* sc4 = (const f32x4*)(modl + b * MODS + scc * DM) + f_lane;
;         u32x2* o8 = (u32x2*)(H + (size_t)row * DM) + f_lane;
; #pragma unroll
;         for (int j = 0; j < 4; ++j) { const f32x4 y = v[j] * rstd * g4[64 * j] * (sc4[64 * j] + 1.0f) + sh4[64 * j];
;             u32x2 w; w.x = cvt_pk_bf16(y.x, y.y); w.y = cvt_pk_bf16(y.z, y.w); o8[64 * j] = w; }
	v_add_f32_e32 v152, v152, v153
	ds_bpermute_b32 v153, v13, v152
	s_waitcnt lgkmcnt(0)
	v_add_f32_e32 v152, v152, v153
	v_fmamk_f32 v152, v152, 0x3a800000, v14
	v_mul_f32_e32 v153, 0x4b800000, v152
	v_cmp_gt_f32_e32 vcc, 0x800000, v152
	s_nop 1
	v_cndmask_b32_e32 v152, v152, v153, vcc
	v_rsq_f32_e32 v152, v152
	s_nop 0
	v_mul_f32_e32 v153, 0x45800000, v152
	v_cndmask_b32_e32 v154, v152, v153, vcc
	s_waitcnt vmcnt(4)
	s_lshl_b32 s10, s4, 11
	s_mov_b32 s11, 0
	v_lshl_add_u64 v[158:159], v[4:5], 0, s[10:11]
	v_mul_f32_e32 v136, v136, v154
	v_mul_f32_e32 v137, v137, v154
	v_mul_f32_e32 v138, v138, v154
	v_mul_f32_e32 v139, v139, v154
	v_mul_f32_e32 v136, v64, v136
	v_mul_f32_e32 v137, v65, v137
	v_mul_f32_e32 v138, v66, v138
	v_mul_f32_e32 v139, v67, v139
	v_add_f32_e32 v104, 1.0, v104
	v_add_f32_e32 v105, 1.0, v105
	v_add_f32_e32 v106, 1.0, v106
	v_add_f32_e32 v107, 1.0, v107
	v_fma_f32 v136, v104, v136, v120
	v_fma_f32 v137, v105, v137, v121
	v_fma_f32 v138, v106, v138, v122
	v_fma_f32 v139, v107, v139, v123
	v_cvt_pk_bf16_f32 v166, v136, v137
	v_cvt_pk_bf16_f32 v167, v138, v139
	global_store_dwordx2 v[158:159], v[166:167], off offset:0
	v_mul_f32_e32 v140, v140, v154
	v_mul_f32_e32 v141, v141, v154
	v_mul_f32_e32 v142, v142, v154
	v_mul_f32_e32 v143, v143, v154
	v_mul_f32_e32 v140, v68, v140
	v_mul_f32_e32 v141, v69, v141
	v_mul_f32_e32 v142, v70, v142
	v_mul_f32_e32 v143, v71, v143
	v_add_f32_e32 v108, 1.0, v108
	v_add_f32_e32 v109, 1.0, v109
	v_add_f32_e32 v110, 1.0, v110
	v_add_f32_e32 v111, 1.0, v111
	v_fma_f32 v140, v108, v140, v124
	v_fma_f32 v141, v109, v141, v125
	v_fma_f32 v142, v110, v142, v126
	v_fma_f32 v143, v111, v143, v127
	v_cvt_pk_bf16_f32 v166, v140, v141
	v_cvt_pk_bf16_f32 v167, v142, v143
	global_store_dwordx2 v[158:159], v[166:167], off offset:512
	v_mul_f32_e32 v144, v144, v154
	v_mul_f32_e32 v145, v145, v154
	v_mul_f32_e32 v146, v146, v154
	v_mul_f32_e32 v147, v147, v154
	v_mul_f32_e32 v144, v72, v144
	v_mul_f32_e32 v145, v73, v145
	v_mul_f32_e32 v146, v74, v146
	v_mul_f32_e32 v147, v75, v147
	v_add_f32_e32 v112, 1.0, v112
	v_add_f32_e32 v113, 1.0, v113
	v_add_f32_e32 v114, 1.0, v114
	v_add_f32_e32 v115, 1.0, v115
	v_fma_f32 v144, v112, v144, v128
	v_fma_f32 v145, v113, v145, v129
	v_fma_f32 v146, v114, v146, v130
	v_fma_f32 v147, v115, v147, v131
	v_cvt_pk_bf16_f32 v166, v144, v145
	v_cvt_pk_bf16_f32 v167, v146, v147
	global_store_dwordx2 v[158:159], v[166:167], off offset:1024
	v_mul_f32_e32 v148, v148, v154
	v_mul_f32_e32 v149, v149, v154
	v_mul_f32_e32 v150, v150, v154
	v_mul_f32_e32 v151, v151, v154
	v_mul_f32_e32 v148, v76, v148
	v_mul_f32_e32 v149, v77, v149
	v_mul_f32_e32 v150, v78, v150
	v_mul_f32_e32 v151, v79, v151
	v_add_f32_e32 v116, 1.0, v116
	v_add_f32_e32 v117, 1.0, v117
	v_add_f32_e32 v118, 1.0, v118
	v_add_f32_e32 v119, 1.0, v119
	v_fma_f32 v148, v116, v148, v132
	v_fma_f32 v149, v117, v149, v133
	v_fma_f32 v150, v118, v150, v134
	v_fma_f32 v151, v119, v151, v135
	v_cvt_pk_bf16_f32 v166, v148, v149
	v_cvt_pk_bf16_f32 v167, v150, v151
	global_store_dwordx2 v[158:159], v[166:167], off offset:1536
	s_add_i32 s4, s4, s5
	s_cmp_lt_i32 s4, 0x8000
	s_cbranch_scc0 .Lmn_p8_done
.Lmn_p8_c1:
	s_ashr_i32 s16, s4, 12
	s_mul_i32 s16, s16, 0x6000
	s_add_u32 s16, s3, s16
	s_addc_u32 s17, s33, 0
	s_add_u32 s100, s16, 0x4000
	s_addc_u32 s101, s17, 0
	v_lshl_add_u64 v[162:163], s[100:101], 0, v[0:1]
	global_load_dwordx4 v[104:107], v[162:163], off offset:0
	global_load_dwordx4 v[108:111], v[162:163], off offset:1024
	global_load_dwordx4 v[112:115], v[162:163], off offset:2048
	global_load_dwordx4 v[116:119], v[162:163], off offset:3072
	s_add_u32 s100, s16, 0x3000
	s_addc_u32 s101, s17, 0
	v_lshl_add_u64 v[164:165], s[100:101], 0, v[0:1]
	global_load_dwordx4 v[120:123], v[164:165], off offset:0
	global_load_dwordx4 v[124:127], v[164:165], off offset:1024
	global_load_dwordx4 v[128:131], v[164:165], off offset:2048
	global_load_dwordx4 v[132:135], v[164:165], off offset:3072
	s_lshl_b32 s10, s5, 1
	s_add_i32 s10, s10, s4
	s_min_i32 s10, s10, 0x7fff
	s_lshl_b32 s10, s10, 11
	s_mov_b32 s11, 0
	v_lshl_add_u64 v[156:157], v[6:7], 0, s[10:11]
	global_load_dwordx2 v[80:81], v[156:157], off offset:0
	global_load_dwordx2 v[82:83], v[156:157], off offset:512
	global_load_dwordx2 v[84:85], v[156:157], off offset:1024
	global_load_dwordx2 v[86:87], v[156:157], off offset:1536
	s_waitcnt vmcnt(20)
	v_lshlrev_b32_e32 v136, 16, v88
	v_and_b32_e32 v137, 0xffff0000, v88
	v_lshlrev_b32_e32 v138, 16, v89
	v_and_b32_e32 v139, 0xffff0000, v89
	v_lshlrev_b32_e32 v140, 16, v90
	v_and_b32_e32 v141, 0xffff0000, v90
	v_lshlrev_b32_e32 v142, 16, v91
	v_and_b32_e32 v143, 0xffff0000, v91
	v_lshlrev_b32_e32 v144, 16, v92
	v_and_b32_e32 v145, 0xffff0000, v92
	v_lshlrev_b32_e32 v146, 16, v93
	v_and_b32_e32 v147, 0xffff0000, v93
	v_lshlrev_b32_e32 v148, 16, v94
	v_and_b32_e32 v149, 0xffff0000, v94
	v_lshlrev_b32_e32 v150, 16, v95
	v_and_b32_e32 v151, 0xffff0000, v95
	v_mul_f32_e32 v152, v136, v136
	v_mul_f32_e32 v153, v137, v137
	v_fmac_f32_e32 v152, v138, v138
	v_fmac_f32_e32 v153, v139, v139
	v_fmac_f32_e32 v152, v140, v140
	v_fmac_f32_e32 v153, v141, v141
	v_fmac_f32_e32 v152, v142, v142
	v_fmac_f32_e32 v153, v143, v143
	v_fmac_f32_e32 v152, v144, v144
	v_fmac_f32_e32 v153, v145, v145
	v_fmac_f32_e32 v152, v146, v146
	v_fmac_f32_e32 v153, v147, v147
	v_fmac_f32_e32 v152, v148, v148
	v_fmac_f32_e32 v153, v149, v149
	v_fmac_f32_e32 v152, v150, v150
	v_fmac_f32_e32 v153, v151, v151
	v_add_f32_e32 v152, v152, v153
	ds_bpermute_b32 v153, v8, v152
	s_waitcnt lgkmcnt(0)
	v_add_f32_e32 v152, v152, v153
	ds_bpermute_b32 v153, v9, v152
	s_waitcnt lgkmcnt(0)
; __device__ __forceinline__ unsigned cvt_pk_bf16(float lo, float hi) { unsigned r; asm volatile("v_cvt_pk_bf16_f32 %0, %1, %2" : "=v"(r) : "v"(lo), "v"(hi)); return r; }
;     ...
;         for (int j = 0; j < 4; ++j) ss += (v[j].x * v[j].x + v[j].y * v[j].y) + (v[j].z * v[j].z + v[j].w * v[j].w);
;         const float rstd = rsqrtf(wave_sum(ss) * (1.0f / DM) + EPS);
;         const f32x4* g4 = (const f32x4*)gnorm + f_lane; const f32x4* sh4 = (const f32x4*)(modl + b * MODS + shc * DM) + f_lane; const f32x4* sc4 = (const f32x4*)(modl + b * MODS + scc * DM) + f_lane;
;         u32x2* o8 = (u32x2*)(H + (size_t)row * DM) + f_lane;
; #pragma unroll
;         for (int j = 0; j < 4; ++j) { const f32x4 y = v[j] * rstd * g4[64 * j] * (sc4[64 * j] + 1.0f) + sh4[64 * j];
;             u32x2 w; w.x = cvt_pk_bf16(y.x, y.y); w.y = cvt_pk_bf16(y.z, y.w); o8[64 * j] = w; }
	v_add_f32_e32 v152, v152, v153
	ds_bpermute_b32 v153, v10, v152
	s_waitcnt lgkmcnt(0)
	v_add_f32_e32 v152, v152, v153
	ds_bpermute_b32 v153, v11, v152
	s_waitcnt lgkmcnt(0)
	v_add_f32_e32 v152, v152, v153
	ds_bpermute_b32 v153, v12, v152
	s_waitcnt lgkmcnt(0)
	v_add_f32_e32 v152, v152, v153
	ds_bpermute_b32 v153, v13, v152
	s_waitcnt lgkmcnt(0)
	v_add_f32_e32 v152, v152, v153
	v_fmamk_f32 v152, v152, 0x3a800000, v14
	v_mul_f32_e32 v153, 0x4b800000, v152
	v_cmp_gt_f32_e32 vcc, 0x800000, v152
	s_nop 1
	v_cndmask_b32_e32 v152, v152, v153, vcc
	v_rsq_f32_e32 v152, v152
	s_nop 0
	v_mul_f32_e32 v153, 0x45800000, v152
	v_cndmask_b32_e32 v154, v152, v153, vcc
	s_waitcnt vmcnt(4)
	s_lshl_b32 s10, s4, 11
	s_mov_b32 s11, 0
	v_lshl_add_u64 v[158:159], v[4:5], 0, s[10:11]
	v_mul_f32_e32 v136, v136, v154
	v_mul_f32_e32 v137, v137, v154
	v_mul_f32_e32 v138, v138, v154
	v_mul_f32_e32 v139, v139, v154
	v_mul_f32_e32 v136, v64, v136
	v_mul_f32_e32 v137, v65, v137
	v_mul_f32_e32 v138, v66, v138
	v_mul_f32_e32 v139, v67, v139
	v_add_f32_e32 v104, 1.0, v104
	v_add_f32_e32 v105, 1.0, v105
	v_add_f32_e32 v106, 1.0, v106
	v_add_f32_e32 v107, 1.0, v107
	v_fma_f32 v136, v104, v136, v120
	v_fma_f32 v137, v105, v137, v121
	v_fma_f32 v138, v106, v138, v122
	v_fma_f32 v139, v107, v139, v123
	v_cvt_pk_bf16_f32 v166, v136, v137
	v_cvt_pk_bf16_f32 v167, v138, v139
	global_store_dwordx2 v[158:159], v[166:167], off offset:0
	v_mul_f32_e32 v140, v140, v154
	v_mul_f32_e32 v141, v141, v154
	v_mul_f32_e32 v142, v142, v154
	v_mul_f32_e32 v143, v143, v154
	v_mul_f32_e32 v140, v68, v140
	v_mul_f32_e32 v141, v69, v141
	v_mul_f32_e32 v142, v70, v142
	v_mul_f32_e32 v143, v71, v143
	v_add_f32_e32 v108, 1.0, v108
	v_add_f32_e32 v109, 1.0, v109
	v_add_f32_e32 v110, 1.0, v110
	v_add_f32_e32 v111, 1.0, v111
	v_fma_f32 v140, v108, v140, v124
	v_fma_f32 v141, v109, v141, v125
	v_fma_f32 v142, v110, v142, v126
	v_fma_f32 v143, v111, v143, v127
	v_cvt_pk_bf16_f32 v166, v140, v141
	v_cvt_pk_bf16_f32 v167, v142, v143
	global_store_dwordx2 v[158:159], v[166:167], off offset:512
	v_mul_f32_e32 v144, v144, v154
	v_mul_f32_e32 v145, v145, v154
	v_mul_f32_e32 v146, v146, v154
	v_mul_f32_e32 v147, v147, v154
	v_mul_f32_e32 v144, v72, v144
	v_mul_f32_e32 v145, v73, v145
	v_mul_f32_e32 v146, v74, v146
	v_mul_f32_e32 v147, v75, v147
	v_add_f32_e32 v112, 1.0, v112
	v_add_f32_e32 v113, 1.0, v113
	v_add_f32_e32 v114, 1.0, v114
	v_add_f32_e32 v115, 1.0, v115
	v_fma_f32 v144, v112, v144, v128
	v_fma_f32 v145, v113, v145, v129
	v_fma_f32 v146, v114, v146, v130
	v_fma_f32 v147, v115, v147, v131
	v_cvt_pk_bf16_f32 v166, v144, v145
	v_cvt_pk_bf16_f32 v167, v146, v147
	global_store_dwordx2 v[158:159], v[166:167], off offset:1024
	v_mul_f32_e32 v148, v148, v154
	v_mul_f32_e32 v149, v149, v154
	v_mul_f32_e32 v150, v150, v154
	v_mul_f32_e32 v151, v151, v154
	v_mul_f32_e32 v148, v76, v148
	v_mul_f32_e32 v149, v77, v149
	v_mul_f32_e32 v150, v78, v150
	v_mul_f32_e32 v151, v79, v151
	v_add_f32_e32 v116, 1.0, v116
	v_add_f32_e32 v117, 1.0, v117
	v_add_f32_e32 v118, 1.0, v118
	v_add_f32_e32 v119, 1.0, v119
	v_fma_f32 v148, v116, v148, v132
	v_fma_f32 v149, v117, v149, v133
	v_fma_f32 v150, v118, v150, v134
	v_fma_f32 v151, v119, v151, v135
	v_cvt_pk_bf16_f32 v166, v148, v149
	v_cvt_pk_bf16_f32 v167, v150, v151
	global_store_dwordx2 v[158:159], v[166:167], off offset:1536
	s_add_i32 s4, s4, s5
	s_cmp_lt_i32 s4, 0x8000
	s_cbranch_scc0 .Lmn_p8_done
.Lmn_p8_c2:
	s_ashr_i32 s16, s4, 12
	s_mul_i32 s16, s16, 0x6000
	s_add_u32 s16, s3, s16
	s_addc_u32 s17, s33, 0
	s_add_u32 s100, s16, 0x4000
	s_addc_u32 s101, s17, 0
	v_lshl_add_u64 v[162:163], s[100:101], 0, v[0:1]
	global_load_dwordx4 v[104:107], v[162:163], off offset:0
	global_load_dwordx4 v[108:111], v[162:163], off offset:1024
	global_load_dwordx4 v[112:115], v[162:163], off offset:2048
	global_load_dwordx4 v[116:119], v[162:163], off offset:3072
	s_add_u32 s100, s16, 0x3000
	s_addc_u32 s101, s17, 0
	v_lshl_add_u64 v[164:165], s[100:101], 0, v[0:1]
	global_load_dwordx4 v[120:123], v[164:165], off offset:0
	global_load_dwordx4 v[124:127], v[164:165], off offset:1024
	global_load_dwordx4 v[128:131], v[164:165], off offset:2048
	global_load_dwordx4 v[132:135], v[164:165], off offset:3072
	s_lshl_b32 s10, s5, 1
	s_add_i32 s10, s10, s4
	s_min_i32 s10, s10, 0x7fff
	s_lshl_b32 s10, s10, 11
	s_mov_b32 s11, 0
	v_lshl_add_u64 v[156:157], v[6:7], 0, s[10:11]
	global_load_dwordx2 v[88:89], v[156:157], off offset:0
	global_load_dwordx2 v[90:91], v[156:157], off offset:512
	global_load_dwordx2 v[92:93], v[156:157], off offset:1024
	global_load_dwordx2 v[94:95], v[156:157], off offset:1536
	s_waitcnt vmcnt(20)
	v_lshlrev_b32_e32 v136, 16, v96
	v_and_b32_e32 v137, 0xffff0000, v96
	v_lshlrev_b32_e32 v138, 16, v97
	v_and_b32_e32 v139, 0xffff0000, v97
	v_lshlrev_b32_e32 v140, 16, v98
	v_and_b32_e32 v141, 0xffff0000, v98
	v_lshlrev_b32_e32 v142, 16, v99
	v_and_b32_e32 v143, 0xffff0000, v99
	v_lshlrev_b32_e32 v144, 16, v100
	v_and_b32_e32 v145, 0xffff0000, v100
	v_lshlrev_b32_e32 v146, 16, v101
	v_and_b32_e32 v147, 0xffff0000, v101
	v_lshlrev_b32_e32 v148, 16, v102
	v_and_b32_e32 v149, 0xffff0000, v102
	v_lshlrev_b32_e32 v150, 16, v103
	v_and_b32_e32 v151, 0xffff0000, v103
	v_mul_f32_e32 v152, v136, v136
	v_mul_f32_e32 v153, v137, v137
	v_fmac_f32_e32 v152, v138, v138
	v_fmac_f32_e32 v153, v139, v139
	v_fmac_f32_e32 v152, v140, v140
	v_fmac_f32_e32 v153, v141, v141
	v_fmac_f32_e32 v152, v142, v142
	v_fmac_f32_e32 v153, v143, v143
	v_fmac_f32_e32 v152, v144, v144
	v_fmac_f32_e32 v153, v145, v145
	v_fmac_f32_e32 v152, v146, v146
	v_fmac_f32_e32 v153, v147, v147
	v_fmac_f32_e32 v152, v148, v148
	v_fmac_f32_e32 v153, v149, v149
	v_fmac_f32_e32 v152, v150, v150
	v_fmac_f32_e32 v153, v151, v151
	v_add_f32_e32 v152, v152, v153
	ds_bpermute_b32 v153, v8, v152
	s_waitcnt lgkmcnt(0)
; __device__ __forceinline__ unsigned cvt_pk_bf16(float lo, float hi) { unsigned r; asm volatile("v_cvt_pk_bf16_f32 %0, %1, %2" : "=v"(r) : "v"(lo), "v"(hi)); return r; }
; __device__ __forceinline__ unsigned xb_ld(unsigned* p)              { return __hip_atomic_load(p, __ATOMIC_RELAXED, __HIP_MEMORY_SCOPE_AGENT); }
;     ...
;         for (int j = 0; j < 4; ++j) ss += (v[j].x * v[j].x + v[j].y * v[j].y) + (v[j].z * v[j].z + v[j].w * v[j].w);
;         const float rstd = rsqrtf(wave_sum(ss) * (1.0f / DM) + EPS);
;         const f32x4* g4 = (const f32x4*)gnorm + f_lane; const f32x4* sh4 = (const f32x4*)(modl + b * MODS + shc * DM) + f_lane; const f32x4* sc4 = (const f32x4*)(modl + b * MODS + scc * DM) + f_lane;
;         u32x2* o8 = (u32x2*)(H + (size_t)row * DM) + f_lane;
; #pragma unroll
;         for (int j = 0; j < 4; ++j) { const f32x4 y = v[j] * rstd * g4[64 * j] * (sc4[64 * j] + 1.0f) + sh4[64 * j];
;             u32x2 w; w.x = cvt_pk_bf16(y.x, y.y); w.y = cvt_pk_bf16(y.z, y.w); o8[64 * j] = w; }
; __device__ __forceinline__ void xcd_barrier_complete(unsigned* bar, unsigned x, unsigned& nloc, unsigned& nx) {
;     const unsigned G = gridDim.x * gridDim.y * gridDim.z;
;     unsigned sum, cnt, mine, sp = 0u;
;     for (;;) {
;         sum = 0u; cnt = 0u; mine = 0u;
; #pragma unroll
;         for (unsigned j = 0; j < 16; ++j) { const unsigned c = xb_ld(&bar[XB_XCNT(j)]); sum += c; cnt += (c > 0u) ? 1u : 0u; mine = (j == x) ? c : mine; }
;         if (sum == G) break;
;         __builtin_amdgcn_s_sleep(1);
;         if ((++sp & 255u) == 0u) { if (xb_ld(&bar[XB_TMO])) break; if (sp > XB_SPIN_CAP) { atomicAdd(&bar[XB_TMO], 1u); break; } }
;     }
;     nloc = mine > 0u ? mine : 1u; nx = cnt > 0u ? cnt : 1u;
; }
; __device__ __forceinline__ void xcd_barrier(const XcdBarrier& b) {
;     asm volatile("s_waitcnt vmcnt(0)" ::: "memory");
;     __syncthreads();
;     if (threadIdx.x == 0) {
;         unsigned* bar = b.bar;
;         __builtin_amdgcn_s_waitcnt(0);
;         unsigned nloc = b.st[0], nx = b.st[1];
;         if (nloc == 0u) { xcd_barrier_complete(bar, b.x, nloc, nx); b.st[0] = nloc; b.st[1] = nx; }
	v_add_f32_e32 v152, v152, v153
	ds_bpermute_b32 v153, v9, v152
	s_waitcnt lgkmcnt(0)
	v_add_f32_e32 v152, v152, v153
	ds_bpermute_b32 v153, v10, v152
	s_waitcnt lgkmcnt(0)
	v_add_f32_e32 v152, v152, v153
	ds_bpermute_b32 v153, v11, v152
	s_waitcnt lgkmcnt(0)
	v_add_f32_e32 v152, v152, v153
	ds_bpermute_b32 v153, v12, v152
	s_waitcnt lgkmcnt(0)
	v_add_f32_e32 v152, v152, v153
	ds_bpermute_b32 v153, v13, v152
	s_waitcnt lgkmcnt(0)
	v_add_f32_e32 v152, v152, v153
	v_fmamk_f32 v152, v152, 0x3a800000, v14
	v_mul_f32_e32 v153, 0x4b800000, v152
	v_cmp_gt_f32_e32 vcc, 0x800000, v152
	s_nop 1
	v_cndmask_b32_e32 v152, v152, v153, vcc
	v_rsq_f32_e32 v152, v152
	s_nop 0
	v_mul_f32_e32 v153, 0x45800000, v152
	v_cndmask_b32_e32 v154, v152, v153, vcc
	s_waitcnt vmcnt(4)
	s_lshl_b32 s10, s4, 11
	s_mov_b32 s11, 0
	v_lshl_add_u64 v[158:159], v[4:5], 0, s[10:11]
	v_mul_f32_e32 v136, v136, v154
	v_mul_f32_e32 v137, v137, v154
	v_mul_f32_e32 v138, v138, v154
	v_mul_f32_e32 v139, v139, v154
	v_mul_f32_e32 v136, v64, v136
	v_mul_f32_e32 v137, v65, v137
	v_mul_f32_e32 v138, v66, v138
	v_mul_f32_e32 v139, v67, v139
	v_add_f32_e32 v104, 1.0, v104
	v_add_f32_e32 v105, 1.0, v105
	v_add_f32_e32 v106, 1.0, v106
	v_add_f32_e32 v107, 1.0, v107
	v_fma_f32 v136, v104, v136, v120
	v_fma_f32 v137, v105, v137, v121
	v_fma_f32 v138, v106, v138, v122
	v_fma_f32 v139, v107, v139, v123
	v_cvt_pk_bf16_f32 v166, v136, v137
	v_cvt_pk_bf16_f32 v167, v138, v139
	global_store_dwordx2 v[158:159], v[166:167], off offset:0
	v_mul_f32_e32 v140, v140, v154
	v_mul_f32_e32 v141, v141, v154
	v_mul_f32_e32 v142, v142, v154
	v_mul_f32_e32 v143, v143, v154
	v_mul_f32_e32 v140, v68, v140
	v_mul_f32_e32 v141, v69, v141
	v_mul_f32_e32 v142, v70, v142
	v_mul_f32_e32 v143, v71, v143
	v_add_f32_e32 v108, 1.0, v108
	v_add_f32_e32 v109, 1.0, v109
	v_add_f32_e32 v110, 1.0, v110
	v_add_f32_e32 v111, 1.0, v111
	v_fma_f32 v140, v108, v140, v124
	v_fma_f32 v141, v109, v141, v125
	v_fma_f32 v142, v110, v142, v126
	v_fma_f32 v143, v111, v143, v127
	v_cvt_pk_bf16_f32 v166, v140, v141
	v_cvt_pk_bf16_f32 v167, v142, v143
	global_store_dwordx2 v[158:159], v[166:167], off offset:512
	v_mul_f32_e32 v144, v144, v154
	v_mul_f32_e32 v145, v145, v154
	v_mul_f32_e32 v146, v146, v154
	v_mul_f32_e32 v147, v147, v154
	v_mul_f32_e32 v144, v72, v144
	v_mul_f32_e32 v145, v73, v145
	v_mul_f32_e32 v146, v74, v146
	v_mul_f32_e32 v147, v75, v147
	v_add_f32_e32 v112, 1.0, v112
	v_add_f32_e32 v113, 1.0, v113
	v_add_f32_e32 v114, 1.0, v114
	v_add_f32_e32 v115, 1.0, v115
	v_fma_f32 v144, v112, v144, v128
	v_fma_f32 v145, v113, v145, v129
	v_fma_f32 v146, v114, v146, v130
	v_fma_f32 v147, v115, v147, v131
	v_cvt_pk_bf16_f32 v166, v144, v145
	v_cvt_pk_bf16_f32 v167, v146, v147
	global_store_dwordx2 v[158:159], v[166:167], off offset:1024
	v_mul_f32_e32 v148, v148, v154
	v_mul_f32_e32 v149, v149, v154
	v_mul_f32_e32 v150, v150, v154
	v_mul_f32_e32 v151, v151, v154
	v_mul_f32_e32 v148, v76, v148
	v_mul_f32_e32 v149, v77, v149
	v_mul_f32_e32 v150, v78, v150
	v_mul_f32_e32 v151, v79, v151
	v_add_f32_e32 v116, 1.0, v116
	v_add_f32_e32 v117, 1.0, v117
	v_add_f32_e32 v118, 1.0, v118
	v_add_f32_e32 v119, 1.0, v119
	v_fma_f32 v148, v116, v148, v132
	v_fma_f32 v149, v117, v149, v133
	v_fma_f32 v150, v118, v150, v134
	v_fma_f32 v151, v119, v151, v135
	v_cvt_pk_bf16_f32 v166, v148, v149
	v_cvt_pk_bf16_f32 v167, v150, v151
	global_store_dwordx2 v[158:159], v[166:167], off offset:1536
	s_add_i32 s4, s4, s5
	s_cmp_lt_i32 s4, 0x8000
	s_cbranch_scc0 .Lmn_p8_done
	s_branch .Lmn_p8_c0
.Lmn_p8_done:
.LBB0_773:
	s_load_dword s4, s[0:1], 0x108
	s_mul_i32 s47, s83, s82
	v_readlane_b32 s8, v251, 0
	v_readlane_b32 s9, v251, 1
	s_mov_b64 s[20:21], s[82:83]
	s_waitcnt lgkmcnt(0)
	s_mul_i32 s47, s47, s4
	s_add_u32 s4, s8, 0x80200
	s_addc_u32 s5, s9, 0
	s_add_u32 s50, s8, 0x80400
	s_addc_u32 s51, s9, 0
	s_add_u32 s56, s8, 0x80500
	s_addc_u32 s57, s9, 0
	s_add_u32 s58, s8, 0x80600
	s_addc_u32 s59, s9, 0
	s_add_u32 s60, s8, 0x80700
	s_addc_u32 s61, s9, 0
	s_add_u32 s62, s8, 0x80800
	s_addc_u32 s63, s9, 0
	s_add_u32 s64, s8, 0x80900
	s_addc_u32 s65, s9, 0
	s_add_u32 s66, s8, 0x80a00
	s_addc_u32 s67, s9, 0
	s_add_u32 s68, s8, 0x80b00
	s_addc_u32 s69, s9, 0
	s_add_u32 s70, s8, 0x80c00
	s_addc_u32 s71, s9, 0
	s_add_u32 s72, s8, 0x80d00
	s_addc_u32 s73, s9, 0
	s_add_u32 s74, s8, 0x80e00
	s_addc_u32 s75, s9, 0
	s_add_u32 s76, s8, 0x80f00
	s_addc_u32 s77, s9, 0
	s_add_u32 s78, s8, 0x81000
	s_addc_u32 s79, s9, 0
	s_add_u32 s80, s8, 0x81100
	s_addc_u32 s81, s9, 0
	s_add_u32 s82, s8, 0x81200
	s_addc_u32 s83, s9, 0
	s_mov_b32 s24, s84
	s_add_u32 s84, s8, 0x81300
	s_addc_u32 s85, s9, 0
	v_readlane_b32 s6, v251, 4
	s_cmp_eq_u32 s6, 15
	s_cselect_b64 s[16:17], -1, 0
	s_cmp_eq_u32 s6, 14
	s_cselect_b64 s[10:11], -1, 0
	v_writelane_b32 v251, s10, 14
	s_cmp_eq_u32 s6, 13
	s_waitcnt vmcnt(0)
	s_waitcnt vmcnt(0)
	v_writelane_b32 v251, s11, 15
	s_cselect_b64 s[10:11], -1, 0
	v_writelane_b32 v251, s10, 16
	s_cmp_eq_u32 s6, 12
	s_barrier
	v_writelane_b32 v251, s11, 17
	s_cselect_b64 s[10:11], -1, 0
	v_writelane_b32 v251, s10, 18
	s_cmp_eq_u32 s6, 11
	s_nop 0
	v_writelane_b32 v251, s11, 19
	s_cselect_b64 s[10:11], -1, 0
	v_writelane_b32 v251, s10, 20
	s_cmp_eq_u32 s6, 10
	s_nop 0
	v_writelane_b32 v251, s11, 21
	s_cselect_b64 s[10:11], -1, 0
	v_writelane_b32 v251, s10, 22
	s_cmp_eq_u32 s6, 9
	s_nop 0
	v_writelane_b32 v251, s11, 23
	s_cselect_b64 s[10:11], -1, 0
	v_writelane_b32 v251, s10, 24
	s_cmp_eq_u32 s6, 8
	s_nop 0
	v_writelane_b32 v251, s11, 25
	s_cselect_b64 s[10:11], -1, 0
	v_writelane_b32 v251, s10, 26
	s_cmp_eq_u32 s6, 7
	s_nop 0
	v_writelane_b32 v251, s11, 27
	s_cselect_b64 s[10:11], -1, 0
	s_cmp_eq_u32 s6, 6
	s_cselect_b64 s[18:19], -1, 0
	s_cmp_eq_u32 s6, 5
	s_cselect_b64 s[14:15], -1, 0
	s_cmp_eq_u32 s6, 4
	s_cselect_b64 s[28:29], -1, 0
	s_cmp_eq_u32 s6, 3
	s_cselect_b64 s[30:31], -1, 0
	s_cmp_eq_u32 s6, 2
	v_writelane_b32 v251, s10, 28
	s_cselect_b64 s[34:35], -1, 0
	s_cmp_eq_u32 s6, 1
	v_writelane_b32 v251, s11, 29
	s_cselect_b64 s[36:37], -1, 0
	s_cmp_eq_u32 s6, 0
	s_cselect_b64 s[38:39], -1, 0
	s_lshl_b32 s6, s6, 8
	v_readlane_b32 s10, v251, 2
	v_readlane_b32 s11, v251, 3
	s_add_u32 s6, s10, s6
	s_addc_u32 s7, s11, 0
	s_add_u32 s48, s6, 0x1400
	s_addc_u32 s49, s7, 0
	s_add_u32 s40, s6, 0x2400
	s_addc_u32 s41, s7, 0
	s_add_u32 s44, s8, 0x83400
	s_addc_u32 s45, s9, 0
	s_add_u32 s42, s8, 0x83500
	s_addc_u32 s43, s9, 0
	s_and_saveexec_b64 s[88:89], s[22:23]
	s_cbranch_execz .LBB0_825
	s_add_i32 s6, 0, 0x20040
	v_mov_b32_e32 v0, s6
	s_waitcnt vmcnt(0) expcnt(0) lgkmcnt(0)
	ds_read_b32 v2, v0
	s_add_i32 s6, 0, 0x20044
	v_mov_b32_e32 v0, s6
	ds_read_b32 v0, v0
	s_waitcnt lgkmcnt(1)
	v_cmp_ne_u32_e32 vcc, 0, v2
	s_cbranch_vccnz .LBB0_789
	s_mov_b32 s8, 1
	v_mov_b32_e32 v16, 0
	s_branch .LBB0_777

; #define LANE_IDS() const int f_tid = tid_(); const int f_lane = f_tid & 63; const int f_gtid = blockIdx.x * (NWAVES * 64) + f_tid; (void)f_lane; (void)f_gtid
;     LANE_IDS();
;     if (F.gw >= wave0) for (int row = row_begin + (F.gw - wave0); row < nrows; row += F.NGW - wave0) {
;         const bool isctx = row >= NLAT; const int b = isctx ? 8 : (row >> 12);
;         const size_t roff = isctx ? (size_t)(row - NLAT) * DM : (size_t)row * DM; const void* sp = isctx ? src_ctx : src_lat;
;         f32x4 v[4]; float ss = 0.f;
;         if (SB) { const u32x2* xr = (const u32x2*)((const bf16*)sp + roff) + f_lane;
; #pragma unroll
;             for (int j = 0; j < 4; ++j) { const u32x2 r = xr[64 * j]; v[j] = (f32x4){__uint_as_float(r.x << 16), __uint_as_float(r.x & 0xffff0000u), __uint_as_float(r.y << 16), __uint_as_float(r.y & 0xffff0000u)}; } }
;         else { const f32x4* xr = (const f32x4*)((const float*)sp + roff) + f_lane;
; #pragma unroll
;             for (int j = 0; j < 4; ++j) v[j] = xr[64 * j]; }
;         if (part != nullptr && isctx) {
;             const f32x4* p0 = (const f32x4*)(part + (size_t)(row - NLAT) * DM) + f_lane; const f32x4* p1 = p0 + (size_t)NCTX * DM / 4; const f32x4* g4p = (const f32x4*)pgate + f_lane;
; #pragma unroll
;             for (int j = 0; j < 4; ++j) v[j] += g4p[64 * j] * (p0[64 * j] + p1[64 * j]); }
; #pragma unroll
;         for (int j = 0; j < 4; ++j) ss += (v[j].x * v[j].x + v[j].y * v[j].y) + (v[j].z * v[j].z + v[j].w * v[j].w);
;         const float rstd = rsqrtf(wave_sum(ss) * (1.0f / DM) + EPS);
.LBB0_1105:
	s_waitcnt lgkmcnt(0)
	s_add_u32 s3, s52, 0x37000
	s_addc_u32 s33, s53, 0
	s_add_u32 s44, s52, 0x6000000
	s_addc_u32 s45, s53, 0
	s_add_u32 s86, s52, 0xe800000
	s_mov_b64 s[22:23], s[80:81]
	s_addc_u32 s87, s53, 0
	s_andn2_b64 vcc, exec, s[8:9]
	s_cbranch_vccnz .LBB0_1109
	s_lshl_b32 s12, s84, 4
	s_cmp_lt_i32 s46, s12
	s_cselect_b64 s[8:9], -1, 0
	s_sub_i32 s4, s46, s12
	s_cmpk_gt_i32 s4, 0x7fff
	s_cselect_b64 s[10:11], -1, 0
	s_or_b64 s[8:9], s[8:9], s[10:11]
	s_mov_b64 s[6:7], s[0:1]
	v_mov_b32_e32 v0, v188
	s_and_b64 vcc, exec, s[8:9]
	s_cbranch_vccnz .LBB0_1109
	v_and_b32_e32 v16, 63, v0
	v_mbcnt_lo_u32_b32 v0, -1, 0
	v_mbcnt_hi_u32_b32 v0, -1, v0
	v_and_b32_e32 v2, 64, v0
	v_add_u32_e32 v2, 64, v2
	v_xor_b32_e32 v3, 1, v0
	v_cmp_lt_i32_e32 vcc, v3, v2
	s_load_dwordx2 s[6:7], s[6:7], 0x30
	v_mov_b32_e32 v1, 0
	v_cndmask_b32_e32 v3, v0, v3, vcc
	v_lshlrev_b32_e32 v8, 2, v3
	v_xor_b32_e32 v3, 2, v0
	v_cmp_lt_i32_e32 vcc, v3, v2
	v_mov_b32_e32 v14, 0x358637bd
	s_mov_b32 s13, 0x800000
	v_cndmask_b32_e32 v3, v0, v3, vcc
	v_lshlrev_b32_e32 v9, 2, v3
	v_xor_b32_e32 v3, 4, v0
	v_cmp_lt_i32_e32 vcc, v3, v2
	s_movk_i32 s14, 0x1000
	v_readlane_b32 s16, v251, 5
	v_cndmask_b32_e32 v3, v0, v3, vcc
	v_lshlrev_b32_e32 v10, 2, v3
	v_xor_b32_e32 v3, 8, v0
	v_cmp_lt_i32_e32 vcc, v3, v2
	v_readlane_b32 s17, v251, 6
	s_nop 0
	v_cndmask_b32_e32 v3, v0, v3, vcc
	v_lshlrev_b32_e32 v11, 2, v3
	v_xor_b32_e32 v3, 16, v0
	v_cmp_lt_i32_e32 vcc, v3, v2
	s_nop 1
	v_cndmask_b32_e32 v3, v0, v3, vcc
	v_lshlrev_b32_e32 v12, 2, v3
	v_xor_b32_e32 v3, 32, v0
	v_cmp_lt_i32_e32 vcc, v3, v2
	s_nop 1
	v_cndmask_b32_e32 v0, v0, v3, vcc
	v_lshlrev_b32_e32 v13, 2, v0
	v_lshlrev_b32_e32 v0, 4, v16
	s_waitcnt lgkmcnt(0)
	v_lshl_add_u64 v[2:3], s[6:7], 0, v[0:1]
	s_mov_b64 s[6:7], 0x1000
	v_lshlrev_b32_e32 v0, 3, v16
	v_lshl_add_u64 v[2:3], v[2:3], 0, s[6:7]
	v_lshl_add_u64 v[4:5], s[86:87], 0, v[0:1]
	v_lshl_add_u64 v[6:7], s[44:45], 0, v[0:1]
	v_lshlrev_b32_e32 v0, 4, v16
	s_sub_i32 s5, s16, s12
	global_load_dwordx4 v[64:67], v[2:3], off offset:0
	global_load_dwordx4 v[68:71], v[2:3], off offset:1024
	global_load_dwordx4 v[72:75], v[2:3], off offset:2048
	global_load_dwordx4 v[76:79], v[2:3], off offset:3072
	s_mov_b32 s8, s4
	s_lshl_b32 s8, s8, 11
	s_mov_b32 s9, 0
	v_lshl_add_u64 v[156:157], v[6:7], 0, s[8:9]
	global_load_dwordx2 v[80:81], v[156:157], off offset:0
	global_load_dwordx2 v[82:83], v[156:157], off offset:512
	global_load_dwordx2 v[84:85], v[156:157], off offset:1024
	global_load_dwordx2 v[86:87], v[156:157], off offset:1536
	s_add_i32 s8, s4, s5
	s_min_i32 s8, s8, 0x7fff
	s_lshl_b32 s8, s8, 11
	s_mov_b32 s9, 0
	v_lshl_add_u64 v[156:157], v[6:7], 0, s[8:9]
	global_load_dwordx2 v[88:89], v[156:157], off offset:0
	global_load_dwordx2 v[90:91], v[156:157], off offset:512
	global_load_dwordx2 v[92:93], v[156:157], off offset:1024
	global_load_dwordx2 v[94:95], v[156:157], off offset:1536
	s_waitcnt vmcnt(4)
.Lmn_p11_c0:
	s_ashr_i32 s10, s4, 12
	s_mul_i32 s10, s10, 0x6000
	s_add_u32 s10, s3, s10
	s_addc_u32 s11, s33, 0
	s_add_u32 s100, s10, 0x1000
	s_addc_u32 s101, s11, 0
	v_lshl_add_u64 v[162:163], s[100:101], 0, v[0:1]
	global_load_dwordx4 v[104:107], v[162:163], off offset:0
	global_load_dwordx4 v[108:111], v[162:163], off offset:1024
	global_load_dwordx4 v[112:115], v[162:163], off offset:2048
	global_load_dwordx4 v[116:119], v[162:163], off offset:3072
	v_lshl_add_u64 v[164:165], s[10:11], 0, v[0:1]
	global_load_dwordx4 v[120:123], v[164:165], off offset:0
	global_load_dwordx4 v[124:127], v[164:165], off offset:1024
	global_load_dwordx4 v[128:131], v[164:165], off offset:2048
	global_load_dwordx4 v[132:135], v[164:165], off offset:3072
	s_lshl_b32 s8, s5, 1
	s_add_i32 s8, s8, s4
	s_min_i32 s8, s8, 0x7fff
	s_lshl_b32 s8, s8, 11
	s_mov_b32 s9, 0
	v_lshl_add_u64 v[156:157], v[6:7], 0, s[8:9]
	global_load_dwordx2 v[96:97], v[156:157], off offset:0
	global_load_dwordx2 v[98:99], v[156:157], off offset:512
	global_load_dwordx2 v[100:101], v[156:157], off offset:1024
	global_load_dwordx2 v[102:103], v[156:157], off offset:1536
	s_waitcnt vmcnt(20)
	v_lshlrev_b32_e32 v136, 16, v80
	v_and_b32_e32 v137, 0xffff0000, v80
	v_lshlrev_b32_e32 v138, 16, v81
	v_and_b32_e32 v139, 0xffff0000, v81
	v_lshlrev_b32_e32 v140, 16, v82
	v_and_b32_e32 v141, 0xffff0000, v82
	v_lshlrev_b32_e32 v142, 16, v83
	v_and_b32_e32 v143, 0xffff0000, v83
	v_lshlrev_b32_e32 v144, 16, v84
	v_and_b32_e32 v145, 0xffff0000, v84
	v_lshlrev_b32_e32 v146, 16, v85
	v_and_b32_e32 v147, 0xffff0000, v85
	v_lshlrev_b32_e32 v148, 16, v86
	v_and_b32_e32 v149, 0xffff0000, v86
	v_lshlrev_b32_e32 v150, 16, v87
	v_and_b32_e32 v151, 0xffff0000, v87
	v_mul_f32_e32 v152, v136, v136
	v_mul_f32_e32 v153, v137, v137
	v_fmac_f32_e32 v152, v138, v138
	v_fmac_f32_e32 v153, v139, v139
	v_fmac_f32_e32 v152, v140, v140
	v_fmac_f32_e32 v153, v141, v141
	v_fmac_f32_e32 v152, v142, v142
	v_fmac_f32_e32 v153, v143, v143
	v_fmac_f32_e32 v152, v144, v144
	v_fmac_f32_e32 v153, v145, v145
	v_fmac_f32_e32 v152, v146, v146
	v_fmac_f32_e32 v153, v147, v147
	v_fmac_f32_e32 v152, v148, v148
	v_fmac_f32_e32 v153, v149, v149
	v_fmac_f32_e32 v152, v150, v150
	v_fmac_f32_e32 v153, v151, v151
	v_add_f32_e32 v152, v152, v153
	ds_bpermute_b32 v153, v8, v152
	s_waitcnt lgkmcnt(0)
	v_add_f32_e32 v152, v152, v153
	ds_bpermute_b32 v153, v9, v152
	s_waitcnt lgkmcnt(0)
	v_add_f32_e32 v152, v152, v153
	ds_bpermute_b32 v153, v10, v152
	s_waitcnt lgkmcnt(0)
	v_add_f32_e32 v152, v152, v153
	ds_bpermute_b32 v153, v11, v152
	s_waitcnt lgkmcnt(0)
	v_add_f32_e32 v152, v152, v153
	ds_bpermute_b32 v153, v12, v152
	s_waitcnt lgkmcnt(0)
; __device__ __forceinline__ unsigned cvt_pk_bf16(float lo, float hi) { unsigned r; asm volatile("v_cvt_pk_bf16_f32 %0, %1, %2" : "=v"(r) : "v"(lo), "v"(hi)); return r; }
;     ...
;         for (int j = 0; j < 4; ++j) ss += (v[j].x * v[j].x + v[j].y * v[j].y) + (v[j].z * v[j].z + v[j].w * v[j].w);
;         const float rstd = rsqrtf(wave_sum(ss) * (1.0f / DM) + EPS);
;         const f32x4* g4 = (const f32x4*)gnorm + f_lane; const f32x4* sh4 = (const f32x4*)(modl + b * MODS + shc * DM) + f_lane; const f32x4* sc4 = (const f32x4*)(modl + b * MODS + scc * DM) + f_lane;
;         u32x2* o8 = (u32x2*)(H + (size_t)row * DM) + f_lane;
; #pragma unroll
;         for (int j = 0; j < 4; ++j) { const f32x4 y = v[j] * rstd * g4[64 * j] * (sc4[64 * j] + 1.0f) + sh4[64 * j];
;             u32x2 w; w.x = cvt_pk_bf16(y.x, y.y); w.y = cvt_pk_bf16(y.z, y.w); o8[64 * j] = w; }
	v_add_f32_e32 v152, v152, v153
	ds_bpermute_b32 v153, v13, v152
	s_waitcnt lgkmcnt(0)
	v_add_f32_e32 v152, v152, v153
	v_fmamk_f32 v152, v152, 0x3a800000, v14
	v_mul_f32_e32 v153, 0x4b800000, v152
	v_cmp_gt_f32_e32 vcc, 0x800000, v152
	s_nop 1
	v_cndmask_b32_e32 v152, v152, v153, vcc
	v_rsq_f32_e32 v152, v152
	s_nop 0
	v_mul_f32_e32 v153, 0x45800000, v152
	v_cndmask_b32_e32 v154, v152, v153, vcc
	s_waitcnt vmcnt(4)
	s_lshl_b32 s8, s4, 11
	s_mov_b32 s9, 0
	v_lshl_add_u64 v[158:159], v[4:5], 0, s[8:9]
	v_mul_f32_e32 v136, v136, v154
	v_mul_f32_e32 v137, v137, v154
	v_mul_f32_e32 v138, v138, v154
	v_mul_f32_e32 v139, v139, v154
	v_mul_f32_e32 v136, v64, v136
	v_mul_f32_e32 v137, v65, v137
	v_mul_f32_e32 v138, v66, v138
	v_mul_f32_e32 v139, v67, v139
	v_add_f32_e32 v104, 1.0, v104
	v_add_f32_e32 v105, 1.0, v105
	v_add_f32_e32 v106, 1.0, v106
	v_add_f32_e32 v107, 1.0, v107
	v_fma_f32 v136, v104, v136, v120
	v_fma_f32 v137, v105, v137, v121
	v_fma_f32 v138, v106, v138, v122
	v_fma_f32 v139, v107, v139, v123
	v_cvt_pk_bf16_f32 v166, v136, v137
	v_cvt_pk_bf16_f32 v167, v138, v139
	global_store_dwordx2 v[158:159], v[166:167], off offset:0
	v_mul_f32_e32 v140, v140, v154
	v_mul_f32_e32 v141, v141, v154
	v_mul_f32_e32 v142, v142, v154
	v_mul_f32_e32 v143, v143, v154
	v_mul_f32_e32 v140, v68, v140
	v_mul_f32_e32 v141, v69, v141
	v_mul_f32_e32 v142, v70, v142
	v_mul_f32_e32 v143, v71, v143
	v_add_f32_e32 v108, 1.0, v108
	v_add_f32_e32 v109, 1.0, v109
	v_add_f32_e32 v110, 1.0, v110
	v_add_f32_e32 v111, 1.0, v111
	v_fma_f32 v140, v108, v140, v124
	v_fma_f32 v141, v109, v141, v125
	v_fma_f32 v142, v110, v142, v126
	v_fma_f32 v143, v111, v143, v127
	v_cvt_pk_bf16_f32 v166, v140, v141
	v_cvt_pk_bf16_f32 v167, v142, v143
	global_store_dwordx2 v[158:159], v[166:167], off offset:512
	v_mul_f32_e32 v144, v144, v154
	v_mul_f32_e32 v145, v145, v154
	v_mul_f32_e32 v146, v146, v154
	v_mul_f32_e32 v147, v147, v154
	v_mul_f32_e32 v144, v72, v144
	v_mul_f32_e32 v145, v73, v145
	v_mul_f32_e32 v146, v74, v146
	v_mul_f32_e32 v147, v75, v147
	v_add_f32_e32 v112, 1.0, v112
	v_add_f32_e32 v113, 1.0, v113
	v_add_f32_e32 v114, 1.0, v114
	v_add_f32_e32 v115, 1.0, v115
	v_fma_f32 v144, v112, v144, v128
	v_fma_f32 v145, v113, v145, v129
	v_fma_f32 v146, v114, v146, v130
	v_fma_f32 v147, v115, v147, v131
	v_cvt_pk_bf16_f32 v166, v144, v145
	v_cvt_pk_bf16_f32 v167, v146, v147
	global_store_dwordx2 v[158:159], v[166:167], off offset:1024
	v_mul_f32_e32 v148, v148, v154
	v_mul_f32_e32 v149, v149, v154
	v_mul_f32_e32 v150, v150, v154
	v_mul_f32_e32 v151, v151, v154
	v_mul_f32_e32 v148, v76, v148
	v_mul_f32_e32 v149, v77, v149
	v_mul_f32_e32 v150, v78, v150
	v_mul_f32_e32 v151, v79, v151
	v_add_f32_e32 v116, 1.0, v116
	v_add_f32_e32 v117, 1.0, v117
	v_add_f32_e32 v118, 1.0, v118
	v_add_f32_e32 v119, 1.0, v119
	v_fma_f32 v148, v116, v148, v132
	v_fma_f32 v149, v117, v149, v133
	v_fma_f32 v150, v118, v150, v134
	v_fma_f32 v151, v119, v151, v135
	v_cvt_pk_bf16_f32 v166, v148, v149
	v_cvt_pk_bf16_f32 v167, v150, v151
	global_store_dwordx2 v[158:159], v[166:167], off offset:1536
	s_add_i32 s4, s4, s5
	s_cmp_lt_i32 s4, 0x8000
	s_cbranch_scc0 .Lmn_p11_done
.Lmn_p11_c1:
	s_ashr_i32 s10, s4, 12
	s_mul_i32 s10, s10, 0x6000
	s_add_u32 s10, s3, s10
	s_addc_u32 s11, s33, 0
	s_add_u32 s100, s10, 0x1000
	s_addc_u32 s101, s11, 0
	v_lshl_add_u64 v[162:163], s[100:101], 0, v[0:1]
	global_load_dwordx4 v[104:107], v[162:163], off offset:0
	global_load_dwordx4 v[108:111], v[162:163], off offset:1024
	global_load_dwordx4 v[112:115], v[162:163], off offset:2048
	global_load_dwordx4 v[116:119], v[162:163], off offset:3072
	v_lshl_add_u64 v[164:165], s[10:11], 0, v[0:1]
	global_load_dwordx4 v[120:123], v[164:165], off offset:0
	global_load_dwordx4 v[124:127], v[164:165], off offset:1024
	global_load_dwordx4 v[128:131], v[164:165], off offset:2048
	global_load_dwordx4 v[132:135], v[164:165], off offset:3072
	s_lshl_b32 s8, s5, 1
	s_add_i32 s8, s8, s4
	s_min_i32 s8, s8, 0x7fff
	s_lshl_b32 s8, s8, 11
	s_mov_b32 s9, 0
	v_lshl_add_u64 v[156:157], v[6:7], 0, s[8:9]
	global_load_dwordx2 v[80:81], v[156:157], off offset:0
	global_load_dwordx2 v[82:83], v[156:157], off offset:512
	global_load_dwordx2 v[84:85], v[156:157], off offset:1024
	global_load_dwordx2 v[86:87], v[156:157], off offset:1536
	s_waitcnt vmcnt(20)
	v_lshlrev_b32_e32 v136, 16, v88
	v_and_b32_e32 v137, 0xffff0000, v88
	v_lshlrev_b32_e32 v138, 16, v89
	v_and_b32_e32 v139, 0xffff0000, v89
	v_lshlrev_b32_e32 v140, 16, v90
	v_and_b32_e32 v141, 0xffff0000, v90
	v_lshlrev_b32_e32 v142, 16, v91
	v_and_b32_e32 v143, 0xffff0000, v91
	v_lshlrev_b32_e32 v144, 16, v92
	v_and_b32_e32 v145, 0xffff0000, v92
	v_lshlrev_b32_e32 v146, 16, v93
	v_and_b32_e32 v147, 0xffff0000, v93
	v_lshlrev_b32_e32 v148, 16, v94
	v_and_b32_e32 v149, 0xffff0000, v94
	v_lshlrev_b32_e32 v150, 16, v95
	v_and_b32_e32 v151, 0xffff0000, v95
	v_mul_f32_e32 v152, v136, v136
	v_mul_f32_e32 v153, v137, v137
	v_fmac_f32_e32 v152, v138, v138
	v_fmac_f32_e32 v153, v139, v139
	v_fmac_f32_e32 v152, v140, v140
	v_fmac_f32_e32 v153, v141, v141
	v_fmac_f32_e32 v152, v142, v142
	v_fmac_f32_e32 v153, v143, v143
	v_fmac_f32_e32 v152, v144, v144
	v_fmac_f32_e32 v153, v145, v145
	v_fmac_f32_e32 v152, v146, v146
	v_fmac_f32_e32 v153, v147, v147
	v_fmac_f32_e32 v152, v148, v148
	v_fmac_f32_e32 v153, v149, v149
	v_fmac_f32_e32 v152, v150, v150
	v_fmac_f32_e32 v153, v151, v151
	v_add_f32_e32 v152, v152, v153
	ds_bpermute_b32 v153, v8, v152
	s_waitcnt lgkmcnt(0)
	v_add_f32_e32 v152, v152, v153
	ds_bpermute_b32 v153, v9, v152
	s_waitcnt lgkmcnt(0)
	v_add_f32_e32 v152, v152, v153
	ds_bpermute_b32 v153, v10, v152
	s_waitcnt lgkmcnt(0)
; __device__ __forceinline__ unsigned cvt_pk_bf16(float lo, float hi) { unsigned r; asm volatile("v_cvt_pk_bf16_f32 %0, %1, %2" : "=v"(r) : "v"(lo), "v"(hi)); return r; }
;     ...
;         for (int j = 0; j < 4; ++j) ss += (v[j].x * v[j].x + v[j].y * v[j].y) + (v[j].z * v[j].z + v[j].w * v[j].w);
;         const float rstd = rsqrtf(wave_sum(ss) * (1.0f / DM) + EPS);
;         const f32x4* g4 = (const f32x4*)gnorm + f_lane; const f32x4* sh4 = (const f32x4*)(modl + b * MODS + shc * DM) + f_lane; const f32x4* sc4 = (const f32x4*)(modl + b * MODS + scc * DM) + f_lane;
;         u32x2* o8 = (u32x2*)(H + (size_t)row * DM) + f_lane;
; #pragma unroll
;         for (int j = 0; j < 4; ++j) { const f32x4 y = v[j] * rstd * g4[64 * j] * (sc4[64 * j] + 1.0f) + sh4[64 * j];
;             u32x2 w; w.x = cvt_pk_bf16(y.x, y.y); w.y = cvt_pk_bf16(y.z, y.w); o8[64 * j] = w; }
	v_add_f32_e32 v152, v152, v153
	ds_bpermute_b32 v153, v11, v152
	s_waitcnt lgkmcnt(0)
	v_add_f32_e32 v152, v152, v153
	ds_bpermute_b32 v153, v12, v152
	s_waitcnt lgkmcnt(0)
	v_add_f32_e32 v152, v152, v153
	ds_bpermute_b32 v153, v13, v152
	s_waitcnt lgkmcnt(0)
	v_add_f32_e32 v152, v152, v153
	v_fmamk_f32 v152, v152, 0x3a800000, v14
	v_mul_f32_e32 v153, 0x4b800000, v152
	v_cmp_gt_f32_e32 vcc, 0x800000, v152
	s_nop 1
	v_cndmask_b32_e32 v152, v152, v153, vcc
	v_rsq_f32_e32 v152, v152
	s_nop 0
	v_mul_f32_e32 v153, 0x45800000, v152
	v_cndmask_b32_e32 v154, v152, v153, vcc
	s_waitcnt vmcnt(4)
	s_lshl_b32 s8, s4, 11
	s_mov_b32 s9, 0
	v_lshl_add_u64 v[158:159], v[4:5], 0, s[8:9]
	v_mul_f32_e32 v136, v136, v154
	v_mul_f32_e32 v137, v137, v154
	v_mul_f32_e32 v138, v138, v154
	v_mul_f32_e32 v139, v139, v154
	v_mul_f32_e32 v136, v64, v136
	v_mul_f32_e32 v137, v65, v137
	v_mul_f32_e32 v138, v66, v138
	v_mul_f32_e32 v139, v67, v139
	v_add_f32_e32 v104, 1.0, v104
	v_add_f32_e32 v105, 1.0, v105
	v_add_f32_e32 v106, 1.0, v106
	v_add_f32_e32 v107, 1.0, v107
	v_fma_f32 v136, v104, v136, v120
	v_fma_f32 v137, v105, v137, v121
	v_fma_f32 v138, v106, v138, v122
	v_fma_f32 v139, v107, v139, v123
	v_cvt_pk_bf16_f32 v166, v136, v137
	v_cvt_pk_bf16_f32 v167, v138, v139
	global_store_dwordx2 v[158:159], v[166:167], off offset:0
	v_mul_f32_e32 v140, v140, v154
	v_mul_f32_e32 v141, v141, v154
	v_mul_f32_e32 v142, v142, v154
	v_mul_f32_e32 v143, v143, v154
	v_mul_f32_e32 v140, v68, v140
	v_mul_f32_e32 v141, v69, v141
	v_mul_f32_e32 v142, v70, v142
	v_mul_f32_e32 v143, v71, v143
	v_add_f32_e32 v108, 1.0, v108
	v_add_f32_e32 v109, 1.0, v109
	v_add_f32_e32 v110, 1.0, v110
	v_add_f32_e32 v111, 1.0, v111
	v_fma_f32 v140, v108, v140, v124
	v_fma_f32 v141, v109, v141, v125
	v_fma_f32 v142, v110, v142, v126
	v_fma_f32 v143, v111, v143, v127
	v_cvt_pk_bf16_f32 v166, v140, v141
	v_cvt_pk_bf16_f32 v167, v142, v143
	global_store_dwordx2 v[158:159], v[166:167], off offset:512
	v_mul_f32_e32 v144, v144, v154
	v_mul_f32_e32 v145, v145, v154
	v_mul_f32_e32 v146, v146, v154
	v_mul_f32_e32 v147, v147, v154
	v_mul_f32_e32 v144, v72, v144
	v_mul_f32_e32 v145, v73, v145
	v_mul_f32_e32 v146, v74, v146
	v_mul_f32_e32 v147, v75, v147
	v_add_f32_e32 v112, 1.0, v112
	v_add_f32_e32 v113, 1.0, v113
	v_add_f32_e32 v114, 1.0, v114
	v_add_f32_e32 v115, 1.0, v115
	v_fma_f32 v144, v112, v144, v128
	v_fma_f32 v145, v113, v145, v129
	v_fma_f32 v146, v114, v146, v130
	v_fma_f32 v147, v115, v147, v131
	v_cvt_pk_bf16_f32 v166, v144, v145
	v_cvt_pk_bf16_f32 v167, v146, v147
	global_store_dwordx2 v[158:159], v[166:167], off offset:1024
	v_mul_f32_e32 v148, v148, v154
	v_mul_f32_e32 v149, v149, v154
	v_mul_f32_e32 v150, v150, v154
	v_mul_f32_e32 v151, v151, v154
	v_mul_f32_e32 v148, v76, v148
	v_mul_f32_e32 v149, v77, v149
	v_mul_f32_e32 v150, v78, v150
	v_mul_f32_e32 v151, v79, v151
	v_add_f32_e32 v116, 1.0, v116
	v_add_f32_e32 v117, 1.0, v117
	v_add_f32_e32 v118, 1.0, v118
	v_add_f32_e32 v119, 1.0, v119
	v_fma_f32 v148, v116, v148, v132
	v_fma_f32 v149, v117, v149, v133
	v_fma_f32 v150, v118, v150, v134
	v_fma_f32 v151, v119, v151, v135
	v_cvt_pk_bf16_f32 v166, v148, v149
	v_cvt_pk_bf16_f32 v167, v150, v151
	global_store_dwordx2 v[158:159], v[166:167], off offset:1536
	s_add_i32 s4, s4, s5
	s_cmp_lt_i32 s4, 0x8000
	s_cbranch_scc0 .Lmn_p11_done
.Lmn_p11_c2:
	s_ashr_i32 s10, s4, 12
	s_mul_i32 s10, s10, 0x6000
	s_add_u32 s10, s3, s10
	s_addc_u32 s11, s33, 0
	s_add_u32 s100, s10, 0x1000
	s_addc_u32 s101, s11, 0
	v_lshl_add_u64 v[162:163], s[100:101], 0, v[0:1]
	global_load_dwordx4 v[104:107], v[162:163], off offset:0
	global_load_dwordx4 v[108:111], v[162:163], off offset:1024
	global_load_dwordx4 v[112:115], v[162:163], off offset:2048
	global_load_dwordx4 v[116:119], v[162:163], off offset:3072
	v_lshl_add_u64 v[164:165], s[10:11], 0, v[0:1]
	global_load_dwordx4 v[120:123], v[164:165], off offset:0
	global_load_dwordx4 v[124:127], v[164:165], off offset:1024
	global_load_dwordx4 v[128:131], v[164:165], off offset:2048
	global_load_dwordx4 v[132:135], v[164:165], off offset:3072
	s_lshl_b32 s8, s5, 1
	s_add_i32 s8, s8, s4
	s_min_i32 s8, s8, 0x7fff
	s_lshl_b32 s8, s8, 11
	s_mov_b32 s9, 0
	v_lshl_add_u64 v[156:157], v[6:7], 0, s[8:9]
	global_load_dwordx2 v[88:89], v[156:157], off offset:0
	global_load_dwordx2 v[90:91], v[156:157], off offset:512
	global_load_dwordx2 v[92:93], v[156:157], off offset:1024
	global_load_dwordx2 v[94:95], v[156:157], off offset:1536
	s_waitcnt vmcnt(20)
	v_lshlrev_b32_e32 v136, 16, v96
	v_and_b32_e32 v137, 0xffff0000, v96
	v_lshlrev_b32_e32 v138, 16, v97
	v_and_b32_e32 v139, 0xffff0000, v97
	v_lshlrev_b32_e32 v140, 16, v98
	v_and_b32_e32 v141, 0xffff0000, v98
	v_lshlrev_b32_e32 v142, 16, v99
	v_and_b32_e32 v143, 0xffff0000, v99
	v_lshlrev_b32_e32 v144, 16, v100
	v_and_b32_e32 v145, 0xffff0000, v100
	v_lshlrev_b32_e32 v146, 16, v101
	v_and_b32_e32 v147, 0xffff0000, v101
	v_lshlrev_b32_e32 v148, 16, v102
	v_and_b32_e32 v149, 0xffff0000, v102
	v_lshlrev_b32_e32 v150, 16, v103
	v_and_b32_e32 v151, 0xffff0000, v103
	v_mul_f32_e32 v152, v136, v136
	v_mul_f32_e32 v153, v137, v137
	v_fmac_f32_e32 v152, v138, v138
	v_fmac_f32_e32 v153, v139, v139
	v_fmac_f32_e32 v152, v140, v140
	v_fmac_f32_e32 v153, v141, v141
	v_fmac_f32_e32 v152, v142, v142
	v_fmac_f32_e32 v153, v143, v143
	v_fmac_f32_e32 v152, v144, v144
	v_fmac_f32_e32 v153, v145, v145
	v_fmac_f32_e32 v152, v146, v146
	v_fmac_f32_e32 v153, v147, v147
	v_fmac_f32_e32 v152, v148, v148
	v_fmac_f32_e32 v153, v149, v149
	v_fmac_f32_e32 v152, v150, v150
	v_fmac_f32_e32 v153, v151, v151
	v_add_f32_e32 v152, v152, v153
	ds_bpermute_b32 v153, v8, v152
	s_waitcnt lgkmcnt(0)
; __device__ __forceinline__ unsigned cvt_pk_bf16(float lo, float hi) { unsigned r; asm volatile("v_cvt_pk_bf16_f32 %0, %1, %2" : "=v"(r) : "v"(lo), "v"(hi)); return r; }
; __device__ __forceinline__ unsigned xb_ld(unsigned* p)              { return __hip_atomic_load(p, __ATOMIC_RELAXED, __HIP_MEMORY_SCOPE_AGENT); }
;     ...
;         for (int j = 0; j < 4; ++j) ss += (v[j].x * v[j].x + v[j].y * v[j].y) + (v[j].z * v[j].z + v[j].w * v[j].w);
;         const float rstd = rsqrtf(wave_sum(ss) * (1.0f / DM) + EPS);
;         const f32x4* g4 = (const f32x4*)gnorm + f_lane; const f32x4* sh4 = (const f32x4*)(modl + b * MODS + shc * DM) + f_lane; const f32x4* sc4 = (const f32x4*)(modl + b * MODS + scc * DM) + f_lane;
;         u32x2* o8 = (u32x2*)(H + (size_t)row * DM) + f_lane;
; #pragma unroll
;         for (int j = 0; j < 4; ++j) { const f32x4 y = v[j] * rstd * g4[64 * j] * (sc4[64 * j] + 1.0f) + sh4[64 * j];
;             u32x2 w; w.x = cvt_pk_bf16(y.x, y.y); w.y = cvt_pk_bf16(y.z, y.w); o8[64 * j] = w; }
; __device__ __forceinline__ void xcd_barrier_complete(unsigned* bar, unsigned x, unsigned& nloc, unsigned& nx) {
;     const unsigned G = gridDim.x * gridDim.y * gridDim.z;
;     unsigned sum, cnt, mine, sp = 0u;
;     for (;;) {
;         sum = 0u; cnt = 0u; mine = 0u;
; #pragma unroll
;         for (unsigned j = 0; j < 16; ++j) { const unsigned c = xb_ld(&bar[XB_XCNT(j)]); sum += c; cnt += (c > 0u) ? 1u : 0u; mine = (j == x) ? c : mine; }
;         if (sum == G) break;
;         __builtin_amdgcn_s_sleep(1);
;         if ((++sp & 255u) == 0u) { if (xb_ld(&bar[XB_TMO])) break; if (sp > XB_SPIN_CAP) { atomicAdd(&bar[XB_TMO], 1u); break; } }
;     }
;     nloc = mine > 0u ? mine : 1u; nx = cnt > 0u ? cnt : 1u;
; }
; __device__ __forceinline__ void xcd_barrier(const XcdBarrier& b) {
;     asm volatile("s_waitcnt vmcnt(0)" ::: "memory");
;     __syncthreads();
;     if (threadIdx.x == 0) {
;         unsigned* bar = b.bar;
;         __builtin_amdgcn_s_waitcnt(0);
;         unsigned nloc = b.st[0], nx = b.st[1];
;         if (nloc == 0u) { xcd_barrier_complete(bar, b.x, nloc, nx); b.st[0] = nloc; b.st[1] = nx; }
	v_add_f32_e32 v152, v152, v153
	ds_bpermute_b32 v153, v9, v152
	s_waitcnt lgkmcnt(0)
	v_add_f32_e32 v152, v152, v153
	ds_bpermute_b32 v153, v10, v152
	s_waitcnt lgkmcnt(0)
	v_add_f32_e32 v152, v152, v153
	ds_bpermute_b32 v153, v11, v152
	s_waitcnt lgkmcnt(0)
	v_add_f32_e32 v152, v152, v153
	ds_bpermute_b32 v153, v12, v152
	s_waitcnt lgkmcnt(0)
	v_add_f32_e32 v152, v152, v153
	ds_bpermute_b32 v153, v13, v152
	s_waitcnt lgkmcnt(0)
	v_add_f32_e32 v152, v152, v153
	v_fmamk_f32 v152, v152, 0x3a800000, v14
	v_mul_f32_e32 v153, 0x4b800000, v152
	v_cmp_gt_f32_e32 vcc, 0x800000, v152
	s_nop 1
	v_cndmask_b32_e32 v152, v152, v153, vcc
	v_rsq_f32_e32 v152, v152
	s_nop 0
	v_mul_f32_e32 v153, 0x45800000, v152
	v_cndmask_b32_e32 v154, v152, v153, vcc
	s_waitcnt vmcnt(4)
	s_lshl_b32 s8, s4, 11
	s_mov_b32 s9, 0
	v_lshl_add_u64 v[158:159], v[4:5], 0, s[8:9]
	v_mul_f32_e32 v136, v136, v154
	v_mul_f32_e32 v137, v137, v154
	v_mul_f32_e32 v138, v138, v154
	v_mul_f32_e32 v139, v139, v154
	v_mul_f32_e32 v136, v64, v136
	v_mul_f32_e32 v137, v65, v137
	v_mul_f32_e32 v138, v66, v138
	v_mul_f32_e32 v139, v67, v139
	v_add_f32_e32 v104, 1.0, v104
	v_add_f32_e32 v105, 1.0, v105
	v_add_f32_e32 v106, 1.0, v106
	v_add_f32_e32 v107, 1.0, v107
	v_fma_f32 v136, v104, v136, v120
	v_fma_f32 v137, v105, v137, v121
	v_fma_f32 v138, v106, v138, v122
	v_fma_f32 v139, v107, v139, v123
	v_cvt_pk_bf16_f32 v166, v136, v137
	v_cvt_pk_bf16_f32 v167, v138, v139
	global_store_dwordx2 v[158:159], v[166:167], off offset:0
	v_mul_f32_e32 v140, v140, v154
	v_mul_f32_e32 v141, v141, v154
	v_mul_f32_e32 v142, v142, v154
	v_mul_f32_e32 v143, v143, v154
	v_mul_f32_e32 v140, v68, v140
	v_mul_f32_e32 v141, v69, v141
	v_mul_f32_e32 v142, v70, v142
	v_mul_f32_e32 v143, v71, v143
	v_add_f32_e32 v108, 1.0, v108
	v_add_f32_e32 v109, 1.0, v109
	v_add_f32_e32 v110, 1.0, v110
	v_add_f32_e32 v111, 1.0, v111
	v_fma_f32 v140, v108, v140, v124
	v_fma_f32 v141, v109, v141, v125
	v_fma_f32 v142, v110, v142, v126
	v_fma_f32 v143, v111, v143, v127
	v_cvt_pk_bf16_f32 v166, v140, v141
	v_cvt_pk_bf16_f32 v167, v142, v143
	global_store_dwordx2 v[158:159], v[166:167], off offset:512
	v_mul_f32_e32 v144, v144, v154
	v_mul_f32_e32 v145, v145, v154
	v_mul_f32_e32 v146, v146, v154
	v_mul_f32_e32 v147, v147, v154
	v_mul_f32_e32 v144, v72, v144
	v_mul_f32_e32 v145, v73, v145
	v_mul_f32_e32 v146, v74, v146
	v_mul_f32_e32 v147, v75, v147
	v_add_f32_e32 v112, 1.0, v112
	v_add_f32_e32 v113, 1.0, v113
	v_add_f32_e32 v114, 1.0, v114
	v_add_f32_e32 v115, 1.0, v115
	v_fma_f32 v144, v112, v144, v128
	v_fma_f32 v145, v113, v145, v129
	v_fma_f32 v146, v114, v146, v130
	v_fma_f32 v147, v115, v147, v131
	v_cvt_pk_bf16_f32 v166, v144, v145
	v_cvt_pk_bf16_f32 v167, v146, v147
	global_store_dwordx2 v[158:159], v[166:167], off offset:1024
	v_mul_f32_e32 v148, v148, v154
	v_mul_f32_e32 v149, v149, v154
	v_mul_f32_e32 v150, v150, v154
	v_mul_f32_e32 v151, v151, v154
	v_mul_f32_e32 v148, v76, v148
	v_mul_f32_e32 v149, v77, v149
	v_mul_f32_e32 v150, v78, v150
	v_mul_f32_e32 v151, v79, v151
	v_add_f32_e32 v116, 1.0, v116
	v_add_f32_e32 v117, 1.0, v117
	v_add_f32_e32 v118, 1.0, v118
	v_add_f32_e32 v119, 1.0, v119
	v_fma_f32 v148, v116, v148, v132
	v_fma_f32 v149, v117, v149, v133
	v_fma_f32 v150, v118, v150, v134
	v_fma_f32 v151, v119, v151, v135
	v_cvt_pk_bf16_f32 v166, v148, v149
	v_cvt_pk_bf16_f32 v167, v150, v151
	global_store_dwordx2 v[158:159], v[166:167], off offset:1536
	s_add_i32 s4, s4, s5
	s_cmp_lt_i32 s4, 0x8000
	s_cbranch_scc0 .Lmn_p11_done
	s_branch .Lmn_p11_c0
.Lmn_p11_done:
.LBB0_1109:
	s_load_dword s4, s[0:1], 0x108
	s_mul_i32 s47, s83, s82
	v_readlane_b32 s8, v251, 0
	v_readlane_b32 s9, v251, 1
	s_mov_b64 s[20:21], s[82:83]
	s_waitcnt lgkmcnt(0)
	s_mul_i32 s47, s47, s4
	s_add_u32 s4, s8, 0x80200
	s_addc_u32 s5, s9, 0
	s_add_u32 s54, s8, 0x80400
	s_addc_u32 s55, s9, 0
	s_add_u32 s56, s8, 0x80500
	s_addc_u32 s57, s9, 0
	s_add_u32 s58, s8, 0x80600
	s_addc_u32 s59, s9, 0
	s_add_u32 s60, s8, 0x80700
	s_addc_u32 s61, s9, 0
	s_add_u32 s62, s8, 0x80800
	s_addc_u32 s63, s9, 0
	s_add_u32 s64, s8, 0x80900
	s_addc_u32 s65, s9, 0
	s_add_u32 s66, s8, 0x80a00
	s_addc_u32 s67, s9, 0
	s_add_u32 s68, s8, 0x80b00
	s_addc_u32 s69, s9, 0
	s_add_u32 s70, s8, 0x80c00
	s_addc_u32 s71, s9, 0
	s_add_u32 s72, s8, 0x80d00
	s_addc_u32 s73, s9, 0
	s_add_u32 s74, s8, 0x80e00
	s_addc_u32 s75, s9, 0
	s_add_u32 s76, s8, 0x80f00
	s_addc_u32 s77, s9, 0
	s_add_u32 s78, s8, 0x81000
	s_addc_u32 s79, s9, 0
	s_add_u32 s80, s8, 0x81100
	s_addc_u32 s81, s9, 0
	s_add_u32 s82, s8, 0x81200
	s_addc_u32 s83, s9, 0
	s_add_u32 s84, s8, 0x81300
	s_addc_u32 s85, s9, 0
	v_readlane_b32 s6, v251, 4
	s_cmp_eq_u32 s6, 15
	s_cselect_b64 s[18:19], -1, 0
	s_cmp_eq_u32 s6, 14
	s_cselect_b64 s[10:11], -1, 0
	v_writelane_b32 v251, s10, 14
	s_cmp_eq_u32 s6, 13
	s_waitcnt vmcnt(0)
	s_waitcnt vmcnt(0)
	v_writelane_b32 v251, s11, 15
	s_cselect_b64 s[10:11], -1, 0
	v_writelane_b32 v251, s10, 16
	s_cmp_eq_u32 s6, 12
	s_barrier
	v_writelane_b32 v251, s11, 17
	s_cselect_b64 s[10:11], -1, 0
	v_writelane_b32 v251, s10, 18
	s_cmp_eq_u32 s6, 11
	s_nop 0
	v_writelane_b32 v251, s11, 19
	s_cselect_b64 s[10:11], -1, 0
	v_writelane_b32 v251, s10, 20
	s_cmp_eq_u32 s6, 10
	s_nop 0
	v_writelane_b32 v251, s11, 21
	s_cselect_b64 s[10:11], -1, 0
	v_writelane_b32 v251, s10, 22
	s_cmp_eq_u32 s6, 9
	s_nop 0
	v_writelane_b32 v251, s11, 23
	s_cselect_b64 s[10:11], -1, 0
	s_cmp_eq_u32 s6, 8
	s_cselect_b64 s[14:15], -1, 0
	s_cmp_eq_u32 s6, 7
	s_cselect_b64 s[16:17], -1, 0
	s_cmp_eq_u32 s6, 6
	s_cselect_b64 s[24:25], -1, 0
	s_cmp_eq_u32 s6, 5
	s_cselect_b64 s[26:27], -1, 0
	s_cmp_eq_u32 s6, 4
	s_cselect_b64 s[28:29], -1, 0
	s_cmp_eq_u32 s6, 3
	s_cselect_b64 s[30:31], -1, 0
	s_cmp_eq_u32 s6, 2
	v_writelane_b32 v251, s10, 24
	s_cselect_b64 s[34:35], -1, 0
	s_cmp_eq_u32 s6, 1
	v_writelane_b32 v251, s11, 25
	s_cselect_b64 s[36:37], -1, 0
	s_cmp_eq_u32 s6, 0
	s_cselect_b64 s[38:39], -1, 0
	s_lshl_b32 s6, s6, 8
	v_readlane_b32 s10, v251, 2
	v_readlane_b32 s11, v251, 3
	s_add_u32 s6, s10, s6
	s_addc_u32 s7, s11, 0
	s_add_u32 s50, s6, 0x1400
	s_addc_u32 s51, s7, 0
	s_add_u32 s40, s6, 0x2400
	s_addc_u32 s41, s7, 0
	s_add_u32 s48, s8, 0x83400
	s_addc_u32 s49, s9, 0
	s_add_u32 s42, s8, 0x83500
	s_addc_u32 s43, s9, 0
	s_and_saveexec_b64 s[88:89], s[22:23]
	s_cbranch_execz .LBB0_1161
	s_add_i32 s6, 0, 0x20040
	v_mov_b32_e32 v0, s6
	s_waitcnt vmcnt(0) expcnt(0) lgkmcnt(0)
	ds_read_b32 v2, v0
	s_add_i32 s6, 0, 0x20044
	v_mov_b32_e32 v0, s6
	ds_read_b32 v0, v0
	s_waitcnt lgkmcnt(1)
	v_cmp_ne_u32_e32 vcc, 0, v2
	s_cbranch_vccnz .LBB0_1125
	s_mov_b32 s8, 1
	v_mov_b32_e32 v16, 0
	s_branch .LBB0_1113

; __device__ __forceinline__ const float* inp(int k) { const CAS cfptr* p = (const CAS cfptr*)__builtin_amdgcn_kernarg_segment_ptr(); asm volatile("" : "+s"(p)); return p[k]; }
; #define LANE_IDS() const int f_tid = tid_(); const int f_lane = f_tid & 63; const int f_gtid = blockIdx.x * (NWAVES * 64) + f_tid; (void)f_lane; (void)f_gtid
; #define IN(k) ((((PH_MASK) >> (k)) & 1u) && kargs()->ph_lo <= (k) && (k) < kargs()->ph_hi)
; #define SEAM(k) do { if (IN((k) + 1)) xcd_barrier(xbar); } while (0)
;     LANE_IDS();
;     if (F.gw >= wave0) for (int row = row_begin + (F.gw - wave0); row < nrows; row += F.NGW - wave0) {
;         const bool isctx = row >= NLAT; const int b = isctx ? 8 : (row >> 12);
;         const size_t roff = isctx ? (size_t)(row - NLAT) * DM : (size_t)row * DM; const void* sp = isctx ? src_ctx : src_lat;
;         f32x4 v[4]; float ss = 0.f;
;         if (SB) { const u32x2* xr = (const u32x2*)((const bf16*)sp + roff) + f_lane;
; #pragma unroll
;             for (int j = 0; j < 4; ++j) { const u32x2 r = xr[64 * j]; v[j] = (f32x4){__uint_as_float(r.x << 16), __uint_as_float(r.x & 0xffff0000u), __uint_as_float(r.y << 16), __uint_as_float(r.y & 0xffff0000u)}; } }
;         else { const f32x4* xr = (const f32x4*)((const float*)sp + roff) + f_lane;
; #pragma unroll
;             for (int j = 0; j < 4; ++j) v[j] = xr[64 * j]; }
;         if (part != nullptr && isctx) {
;             const f32x4* p0 = (const f32x4*)(part + (size_t)(row - NLAT) * DM) + f_lane; const f32x4* p1 = p0 + (size_t)NCTX * DM / 4; const f32x4* g4p = (const f32x4*)pgate + f_lane;
; #pragma unroll
;             for (int j = 0; j < 4; ++j) v[j] += g4p[64 * j] * (p0[64 * j] + p1[64 * j]); }
; #pragma unroll
;         for (int j = 0; j < 4; ++j) ss += (v[j].x * v[j].x + v[j].y * v[j].y) + (v[j].z * v[j].z + v[j].w * v[j].w);
;         const float rstd = rsqrtf(wave_sum(ss) * (1.0f / DM) + EPS);
; __global__ void __launch_bounds__(NWAVES * 64, 2) mk_fwd(Args args) {
;     ...
;     if (IN(18)) for (int rep_ = 0; rep_ < PH_REPS(18); ++rep_) { PH_PTRS(); modnorm_rows<true>(F, X + (size_t)NTOK * DM, X + (size_t)NTOK * DM, NLAT, H, inp(7) + DM, mod1, 3, 4); if (rep_ == PH_REPS(18) - 1) SEAM(18); }
.LBB0_1741:
	s_mov_b64 s[4:5], s[0:1]
	s_load_dword s3, s[4:5], 0xf8
	s_waitcnt lgkmcnt(0)
	s_cmp_gt_i32 s3, 18
	s_cbranch_scc1 .LBB0_1801
	s_mov_b64 s[4:5], s[0:1]
	s_load_dword s3, s[4:5], 0xfc
	s_waitcnt lgkmcnt(0)
	s_cmp_lt_i32 s3, 19
	s_cbranch_scc1 .LBB0_1801
	s_mov_b64 s[4:5], s[0:1]
	s_mov_b64 s[6:7], s[0:1]
	s_cmpk_gt_u32 s46, 0x7fff
	s_mov_b64 s[6:7], s[0:1]
	v_mov_b32_e32 v0, v188
	s_cbranch_scc1 .LBB0_1746
	v_and_b32_e32 v16, 63, v0
	v_mbcnt_lo_u32_b32 v0, -1, 0
	v_mbcnt_hi_u32_b32 v0, -1, v0
	v_and_b32_e32 v2, 64, v0
	v_add_u32_e32 v2, 64, v2
	v_xor_b32_e32 v3, 1, v0
	v_cmp_lt_i32_e32 vcc, v3, v2
	s_load_dwordx2 s[8:9], s[4:5], 0xf0
	s_load_dwordx2 s[12:13], s[6:7], 0x38
	v_cndmask_b32_e32 v3, v0, v3, vcc
	v_lshlrev_b32_e32 v8, 2, v3
	v_xor_b32_e32 v3, 2, v0
	v_cmp_lt_i32_e32 vcc, v3, v2
	v_mov_b32_e32 v1, 0
	s_mov_b64 s[4:5], 0x1000
	v_cndmask_b32_e32 v3, v0, v3, vcc
	v_lshlrev_b32_e32 v9, 2, v3
	v_xor_b32_e32 v3, 4, v0
	v_cmp_lt_i32_e32 vcc, v3, v2
	s_waitcnt lgkmcnt(0)
	s_add_u32 s3, s8, 0x37000
	s_addc_u32 s10, s9, 0
	v_cndmask_b32_e32 v3, v0, v3, vcc
	v_lshlrev_b32_e32 v10, 2, v3
	v_xor_b32_e32 v3, 8, v0
	v_cmp_lt_i32_e32 vcc, v3, v2
	v_mov_b32_e32 v14, 0x358637bd
	s_mov_b32 s11, 0x800000
	v_cndmask_b32_e32 v3, v0, v3, vcc
	v_lshlrev_b32_e32 v11, 2, v3
	v_xor_b32_e32 v3, 16, v0
	v_cmp_lt_i32_e32 vcc, v3, v2
	s_mov_b64 s[6:7], 0x4000
	s_nop 0
	v_cndmask_b32_e32 v3, v0, v3, vcc
	v_lshlrev_b32_e32 v12, 2, v3
	v_xor_b32_e32 v3, 32, v0
	v_cmp_lt_i32_e32 vcc, v3, v2
	s_nop 1
	v_cndmask_b32_e32 v0, v0, v3, vcc
	v_lshlrev_b32_e32 v13, 2, v0
	v_lshlrev_b32_e32 v0, 4, v16
	v_lshl_add_u64 v[2:3], s[12:13], 0, v[0:1]
	v_lshlrev_b32_e32 v0, 3, v16
	v_lshl_add_u64 v[2:3], v[2:3], 0, s[4:5]
	v_lshl_add_u64 v[6:7], s[8:9], 0, v[0:1]
	s_mov_b64 s[4:5], 0xe800000
	v_lshl_add_u64 v[4:5], v[6:7], 0, s[4:5]
	s_mov_b64 s[4:5], 0xa400000
	v_lshl_add_u64 v[6:7], v[6:7], 0, s[4:5]
	v_lshlrev_b32_e32 v0, 4, v16
	s_mov_b64 s[4:5], 0x3000
	s_movk_i32 s12, 0x4000
	s_movk_i32 s13, 0x3000
	global_load_dwordx4 v[64:67], v[2:3], off offset:0
	global_load_dwordx4 v[68:71], v[2:3], off offset:1024
	global_load_dwordx4 v[72:75], v[2:3], off offset:2048
	global_load_dwordx4 v[76:79], v[2:3], off offset:3072
	s_mov_b32 s8, s46
	s_lshl_b32 s8, s8, 11
	s_mov_b32 s9, 0
	v_lshl_add_u64 v[156:157], v[6:7], 0, s[8:9]
	global_load_dwordx2 v[80:81], v[156:157], off offset:0
	global_load_dwordx2 v[82:83], v[156:157], off offset:512
	global_load_dwordx2 v[84:85], v[156:157], off offset:1024
	global_load_dwordx2 v[86:87], v[156:157], off offset:1536
	s_add_i32 s8, s46, s76
	s_min_i32 s8, s8, 0x7fff
	s_lshl_b32 s8, s8, 11
	s_mov_b32 s9, 0
	v_lshl_add_u64 v[156:157], v[6:7], 0, s[8:9]
	global_load_dwordx2 v[88:89], v[156:157], off offset:0
	global_load_dwordx2 v[90:91], v[156:157], off offset:512
	global_load_dwordx2 v[92:93], v[156:157], off offset:1024
	global_load_dwordx2 v[94:95], v[156:157], off offset:1536
	s_waitcnt vmcnt(4)
.Lmn_p18_c0:
	s_ashr_i32 s14, s46, 12
	s_mul_i32 s14, s14, 0x6000
	s_add_u32 s14, s3, s14
	s_addc_u32 s15, s10, 0
	s_add_u32 s100, s14, 0x4000
	s_addc_u32 s101, s15, 0
	v_lshl_add_u64 v[162:163], s[100:101], 0, v[0:1]
	global_load_dwordx4 v[104:107], v[162:163], off offset:0
	global_load_dwordx4 v[108:111], v[162:163], off offset:1024
	global_load_dwordx4 v[112:115], v[162:163], off offset:2048
	global_load_dwordx4 v[116:119], v[162:163], off offset:3072
	s_add_u32 s100, s14, 0x3000
	s_addc_u32 s101, s15, 0
	v_lshl_add_u64 v[164:165], s[100:101], 0, v[0:1]
	global_load_dwordx4 v[120:123], v[164:165], off offset:0
	global_load_dwordx4 v[124:127], v[164:165], off offset:1024
	global_load_dwordx4 v[128:131], v[164:165], off offset:2048
	global_load_dwordx4 v[132:135], v[164:165], off offset:3072
	s_lshl_b32 s8, s76, 1
	s_add_i32 s8, s8, s46
	s_min_i32 s8, s8, 0x7fff
	s_lshl_b32 s8, s8, 11
	s_mov_b32 s9, 0
	v_lshl_add_u64 v[156:157], v[6:7], 0, s[8:9]
	global_load_dwordx2 v[96:97], v[156:157], off offset:0
	global_load_dwordx2 v[98:99], v[156:157], off offset:512
	global_load_dwordx2 v[100:101], v[156:157], off offset:1024
	global_load_dwordx2 v[102:103], v[156:157], off offset:1536
	s_waitcnt vmcnt(20)
	v_lshlrev_b32_e32 v136, 16, v80
	v_and_b32_e32 v137, 0xffff0000, v80
	v_lshlrev_b32_e32 v138, 16, v81
	v_and_b32_e32 v139, 0xffff0000, v81
	v_lshlrev_b32_e32 v140, 16, v82
	v_and_b32_e32 v141, 0xffff0000, v82
	v_lshlrev_b32_e32 v142, 16, v83
	v_and_b32_e32 v143, 0xffff0000, v83
	v_lshlrev_b32_e32 v144, 16, v84
	v_and_b32_e32 v145, 0xffff0000, v84
	v_lshlrev_b32_e32 v146, 16, v85
	v_and_b32_e32 v147, 0xffff0000, v85
	v_lshlrev_b32_e32 v148, 16, v86
	v_and_b32_e32 v149, 0xffff0000, v86
	v_lshlrev_b32_e32 v150, 16, v87
	v_and_b32_e32 v151, 0xffff0000, v87
	v_mul_f32_e32 v152, v136, v136
	v_mul_f32_e32 v153, v137, v137
	v_fmac_f32_e32 v152, v138, v138
	v_fmac_f32_e32 v153, v139, v139
	v_fmac_f32_e32 v152, v140, v140
	v_fmac_f32_e32 v153, v141, v141
	v_fmac_f32_e32 v152, v142, v142
	v_fmac_f32_e32 v153, v143, v143
	v_fmac_f32_e32 v152, v144, v144
	v_fmac_f32_e32 v153, v145, v145
	v_fmac_f32_e32 v152, v146, v146
	v_fmac_f32_e32 v153, v147, v147
	v_fmac_f32_e32 v152, v148, v148
	v_fmac_f32_e32 v153, v149, v149
	v_fmac_f32_e32 v152, v150, v150
	v_fmac_f32_e32 v153, v151, v151
	v_add_f32_e32 v152, v152, v153
	ds_bpermute_b32 v153, v8, v152
	s_waitcnt lgkmcnt(0)
	v_add_f32_e32 v152, v152, v153
	ds_bpermute_b32 v153, v9, v152
	s_waitcnt lgkmcnt(0)
	v_add_f32_e32 v152, v152, v153
	ds_bpermute_b32 v153, v10, v152
	s_waitcnt lgkmcnt(0)
	v_add_f32_e32 v152, v152, v153
	ds_bpermute_b32 v153, v11, v152
	s_waitcnt lgkmcnt(0)
; __device__ __forceinline__ unsigned cvt_pk_bf16(float lo, float hi) { unsigned r; asm volatile("v_cvt_pk_bf16_f32 %0, %1, %2" : "=v"(r) : "v"(lo), "v"(hi)); return r; }
;     ...
;         for (int j = 0; j < 4; ++j) ss += (v[j].x * v[j].x + v[j].y * v[j].y) + (v[j].z * v[j].z + v[j].w * v[j].w);
;         const float rstd = rsqrtf(wave_sum(ss) * (1.0f / DM) + EPS);
;         const f32x4* g4 = (const f32x4*)gnorm + f_lane; const f32x4* sh4 = (const f32x4*)(modl + b * MODS + shc * DM) + f_lane; const f32x4* sc4 = (const f32x4*)(modl + b * MODS + scc * DM) + f_lane;
;         u32x2* o8 = (u32x2*)(H + (size_t)row * DM) + f_lane;
; #pragma unroll
;         for (int j = 0; j < 4; ++j) { const f32x4 y = v[j] * rstd * g4[64 * j] * (sc4[64 * j] + 1.0f) + sh4[64 * j];
;             u32x2 w; w.x = cvt_pk_bf16(y.x, y.y); w.y = cvt_pk_bf16(y.z, y.w); o8[64 * j] = w; }
	v_add_f32_e32 v152, v152, v153
	ds_bpermute_b32 v153, v12, v152
	s_waitcnt lgkmcnt(0)
	v_add_f32_e32 v152, v152, v153
	ds_bpermute_b32 v153, v13, v152
	s_waitcnt lgkmcnt(0)
	v_add_f32_e32 v152, v152, v153
	v_fmamk_f32 v152, v152, 0x3a800000, v14
	v_mul_f32_e32 v153, 0x4b800000, v152
	v_cmp_gt_f32_e32 vcc, 0x800000, v152
	s_nop 1
	v_cndmask_b32_e32 v152, v152, v153, vcc
	v_rsq_f32_e32 v152, v152
	s_nop 0
	v_mul_f32_e32 v153, 0x45800000, v152
	v_cndmask_b32_e32 v154, v152, v153, vcc
	s_waitcnt vmcnt(4)
	s_lshl_b32 s8, s46, 11
	s_mov_b32 s9, 0
	v_lshl_add_u64 v[158:159], v[4:5], 0, s[8:9]
	v_mul_f32_e32 v136, v136, v154
	v_mul_f32_e32 v137, v137, v154
	v_mul_f32_e32 v138, v138, v154
	v_mul_f32_e32 v139, v139, v154
	v_mul_f32_e32 v136, v64, v136
	v_mul_f32_e32 v137, v65, v137
	v_mul_f32_e32 v138, v66, v138
	v_mul_f32_e32 v139, v67, v139
	v_add_f32_e32 v104, 1.0, v104
	v_add_f32_e32 v105, 1.0, v105
	v_add_f32_e32 v106, 1.0, v106
	v_add_f32_e32 v107, 1.0, v107
	v_fma_f32 v136, v104, v136, v120
	v_fma_f32 v137, v105, v137, v121
	v_fma_f32 v138, v106, v138, v122
	v_fma_f32 v139, v107, v139, v123
	v_cvt_pk_bf16_f32 v166, v136, v137
	v_cvt_pk_bf16_f32 v167, v138, v139
	global_store_dwordx2 v[158:159], v[166:167], off offset:0
	v_mul_f32_e32 v140, v140, v154
	v_mul_f32_e32 v141, v141, v154
	v_mul_f32_e32 v142, v142, v154
	v_mul_f32_e32 v143, v143, v154
	v_mul_f32_e32 v140, v68, v140
	v_mul_f32_e32 v141, v69, v141
	v_mul_f32_e32 v142, v70, v142
	v_mul_f32_e32 v143, v71, v143
	v_add_f32_e32 v108, 1.0, v108
	v_add_f32_e32 v109, 1.0, v109
	v_add_f32_e32 v110, 1.0, v110
	v_add_f32_e32 v111, 1.0, v111
	v_fma_f32 v140, v108, v140, v124
	v_fma_f32 v141, v109, v141, v125
	v_fma_f32 v142, v110, v142, v126
	v_fma_f32 v143, v111, v143, v127
	v_cvt_pk_bf16_f32 v166, v140, v141
	v_cvt_pk_bf16_f32 v167, v142, v143
	global_store_dwordx2 v[158:159], v[166:167], off offset:512
	v_mul_f32_e32 v144, v144, v154
	v_mul_f32_e32 v145, v145, v154
	v_mul_f32_e32 v146, v146, v154
	v_mul_f32_e32 v147, v147, v154
	v_mul_f32_e32 v144, v72, v144
	v_mul_f32_e32 v145, v73, v145
	v_mul_f32_e32 v146, v74, v146
	v_mul_f32_e32 v147, v75, v147
	v_add_f32_e32 v112, 1.0, v112
	v_add_f32_e32 v113, 1.0, v113
	v_add_f32_e32 v114, 1.0, v114
	v_add_f32_e32 v115, 1.0, v115
	v_fma_f32 v144, v112, v144, v128
	v_fma_f32 v145, v113, v145, v129
	v_fma_f32 v146, v114, v146, v130
	v_fma_f32 v147, v115, v147, v131
	v_cvt_pk_bf16_f32 v166, v144, v145
	v_cvt_pk_bf16_f32 v167, v146, v147
	global_store_dwordx2 v[158:159], v[166:167], off offset:1024
	v_mul_f32_e32 v148, v148, v154
	v_mul_f32_e32 v149, v149, v154
	v_mul_f32_e32 v150, v150, v154
	v_mul_f32_e32 v151, v151, v154
	v_mul_f32_e32 v148, v76, v148
	v_mul_f32_e32 v149, v77, v149
	v_mul_f32_e32 v150, v78, v150
	v_mul_f32_e32 v151, v79, v151
	v_add_f32_e32 v116, 1.0, v116
	v_add_f32_e32 v117, 1.0, v117
	v_add_f32_e32 v118, 1.0, v118
	v_add_f32_e32 v119, 1.0, v119
	v_fma_f32 v148, v116, v148, v132
	v_fma_f32 v149, v117, v149, v133
	v_fma_f32 v150, v118, v150, v134
	v_fma_f32 v151, v119, v151, v135
	v_cvt_pk_bf16_f32 v166, v148, v149
	v_cvt_pk_bf16_f32 v167, v150, v151
	global_store_dwordx2 v[158:159], v[166:167], off offset:1536
	s_add_i32 s46, s46, s76
	s_cmp_lt_i32 s46, 0x8000
	s_cbranch_scc0 .Lmn_p18_done
.Lmn_p18_c1:
	s_ashr_i32 s14, s46, 12
	s_mul_i32 s14, s14, 0x6000
	s_add_u32 s14, s3, s14
	s_addc_u32 s15, s10, 0
	s_add_u32 s100, s14, 0x4000
	s_addc_u32 s101, s15, 0
	v_lshl_add_u64 v[162:163], s[100:101], 0, v[0:1]
	global_load_dwordx4 v[104:107], v[162:163], off offset:0
	global_load_dwordx4 v[108:111], v[162:163], off offset:1024
	global_load_dwordx4 v[112:115], v[162:163], off offset:2048
	global_load_dwordx4 v[116:119], v[162:163], off offset:3072
	s_add_u32 s100, s14, 0x3000
	s_addc_u32 s101, s15, 0
	v_lshl_add_u64 v[164:165], s[100:101], 0, v[0:1]
	global_load_dwordx4 v[120:123], v[164:165], off offset:0
	global_load_dwordx4 v[124:127], v[164:165], off offset:1024
	global_load_dwordx4 v[128:131], v[164:165], off offset:2048
	global_load_dwordx4 v[132:135], v[164:165], off offset:3072
	s_lshl_b32 s8, s76, 1
	s_add_i32 s8, s8, s46
	s_min_i32 s8, s8, 0x7fff
	s_lshl_b32 s8, s8, 11
	s_mov_b32 s9, 0
	v_lshl_add_u64 v[156:157], v[6:7], 0, s[8:9]
	global_load_dwordx2 v[80:81], v[156:157], off offset:0
	global_load_dwordx2 v[82:83], v[156:157], off offset:512
	global_load_dwordx2 v[84:85], v[156:157], off offset:1024
	global_load_dwordx2 v[86:87], v[156:157], off offset:1536
	s_waitcnt vmcnt(20)
	v_lshlrev_b32_e32 v136, 16, v88
	v_and_b32_e32 v137, 0xffff0000, v88
	v_lshlrev_b32_e32 v138, 16, v89
	v_and_b32_e32 v139, 0xffff0000, v89
	v_lshlrev_b32_e32 v140, 16, v90
	v_and_b32_e32 v141, 0xffff0000, v90
	v_lshlrev_b32_e32 v142, 16, v91
	v_and_b32_e32 v143, 0xffff0000, v91
	v_lshlrev_b32_e32 v144, 16, v92
	v_and_b32_e32 v145, 0xffff0000, v92
	v_lshlrev_b32_e32 v146, 16, v93
	v_and_b32_e32 v147, 0xffff0000, v93
	v_lshlrev_b32_e32 v148, 16, v94
	v_and_b32_e32 v149, 0xffff0000, v94
	v_lshlrev_b32_e32 v150, 16, v95
	v_and_b32_e32 v151, 0xffff0000, v95
	v_mul_f32_e32 v152, v136, v136
	v_mul_f32_e32 v153, v137, v137
	v_fmac_f32_e32 v152, v138, v138
	v_fmac_f32_e32 v153, v139, v139
	v_fmac_f32_e32 v152, v140, v140
	v_fmac_f32_e32 v153, v141, v141
	v_fmac_f32_e32 v152, v142, v142
	v_fmac_f32_e32 v153, v143, v143
	v_fmac_f32_e32 v152, v144, v144
	v_fmac_f32_e32 v153, v145, v145
	v_fmac_f32_e32 v152, v146, v146
	v_fmac_f32_e32 v153, v147, v147
	v_fmac_f32_e32 v152, v148, v148
	v_fmac_f32_e32 v153, v149, v149
	v_fmac_f32_e32 v152, v150, v150
	v_fmac_f32_e32 v153, v151, v151
	v_add_f32_e32 v152, v152, v153
	ds_bpermute_b32 v153, v8, v152
	s_waitcnt lgkmcnt(0)
; __device__ __forceinline__ unsigned cvt_pk_bf16(float lo, float hi) { unsigned r; asm volatile("v_cvt_pk_bf16_f32 %0, %1, %2" : "=v"(r) : "v"(lo), "v"(hi)); return r; }
;     ...
;         for (int j = 0; j < 4; ++j) ss += (v[j].x * v[j].x + v[j].y * v[j].y) + (v[j].z * v[j].z + v[j].w * v[j].w);
;         const float rstd = rsqrtf(wave_sum(ss) * (1.0f / DM) + EPS);
;         const f32x4* g4 = (const f32x4*)gnorm + f_lane; const f32x4* sh4 = (const f32x4*)(modl + b * MODS + shc * DM) + f_lane; const f32x4* sc4 = (const f32x4*)(modl + b * MODS + scc * DM) + f_lane;
;         u32x2* o8 = (u32x2*)(H + (size_t)row * DM) + f_lane;
; #pragma unroll
;         for (int j = 0; j < 4; ++j) { const f32x4 y = v[j] * rstd * g4[64 * j] * (sc4[64 * j] + 1.0f) + sh4[64 * j];
;             u32x2 w; w.x = cvt_pk_bf16(y.x, y.y); w.y = cvt_pk_bf16(y.z, y.w); o8[64 * j] = w; }
	v_add_f32_e32 v152, v152, v153
	ds_bpermute_b32 v153, v9, v152
	s_waitcnt lgkmcnt(0)
	v_add_f32_e32 v152, v152, v153
	ds_bpermute_b32 v153, v10, v152
	s_waitcnt lgkmcnt(0)
	v_add_f32_e32 v152, v152, v153
	ds_bpermute_b32 v153, v11, v152
	s_waitcnt lgkmcnt(0)
	v_add_f32_e32 v152, v152, v153
	ds_bpermute_b32 v153, v12, v152
	s_waitcnt lgkmcnt(0)
	v_add_f32_e32 v152, v152, v153
	ds_bpermute_b32 v153, v13, v152
	s_waitcnt lgkmcnt(0)
	v_add_f32_e32 v152, v152, v153
	v_fmamk_f32 v152, v152, 0x3a800000, v14
	v_mul_f32_e32 v153, 0x4b800000, v152
	v_cmp_gt_f32_e32 vcc, 0x800000, v152
	s_nop 1
	v_cndmask_b32_e32 v152, v152, v153, vcc
	v_rsq_f32_e32 v152, v152
	s_nop 0
	v_mul_f32_e32 v153, 0x45800000, v152
	v_cndmask_b32_e32 v154, v152, v153, vcc
	s_waitcnt vmcnt(4)
	s_lshl_b32 s8, s46, 11
	s_mov_b32 s9, 0
	v_lshl_add_u64 v[158:159], v[4:5], 0, s[8:9]
	v_mul_f32_e32 v136, v136, v154
	v_mul_f32_e32 v137, v137, v154
	v_mul_f32_e32 v138, v138, v154
	v_mul_f32_e32 v139, v139, v154
	v_mul_f32_e32 v136, v64, v136
	v_mul_f32_e32 v137, v65, v137
	v_mul_f32_e32 v138, v66, v138
	v_mul_f32_e32 v139, v67, v139
	v_add_f32_e32 v104, 1.0, v104
	v_add_f32_e32 v105, 1.0, v105
	v_add_f32_e32 v106, 1.0, v106
	v_add_f32_e32 v107, 1.0, v107
	v_fma_f32 v136, v104, v136, v120
	v_fma_f32 v137, v105, v137, v121
	v_fma_f32 v138, v106, v138, v122
	v_fma_f32 v139, v107, v139, v123
	v_cvt_pk_bf16_f32 v166, v136, v137
	v_cvt_pk_bf16_f32 v167, v138, v139
	global_store_dwordx2 v[158:159], v[166:167], off offset:0
	v_mul_f32_e32 v140, v140, v154
	v_mul_f32_e32 v141, v141, v154
	v_mul_f32_e32 v142, v142, v154
	v_mul_f32_e32 v143, v143, v154
	v_mul_f32_e32 v140, v68, v140
	v_mul_f32_e32 v141, v69, v141
	v_mul_f32_e32 v142, v70, v142
	v_mul_f32_e32 v143, v71, v143
	v_add_f32_e32 v108, 1.0, v108
	v_add_f32_e32 v109, 1.0, v109
	v_add_f32_e32 v110, 1.0, v110
	v_add_f32_e32 v111, 1.0, v111
	v_fma_f32 v140, v108, v140, v124
	v_fma_f32 v141, v109, v141, v125
	v_fma_f32 v142, v110, v142, v126
	v_fma_f32 v143, v111, v143, v127
	v_cvt_pk_bf16_f32 v166, v140, v141
	v_cvt_pk_bf16_f32 v167, v142, v143
	global_store_dwordx2 v[158:159], v[166:167], off offset:512
	v_mul_f32_e32 v144, v144, v154
	v_mul_f32_e32 v145, v145, v154
	v_mul_f32_e32 v146, v146, v154
	v_mul_f32_e32 v147, v147, v154
	v_mul_f32_e32 v144, v72, v144
	v_mul_f32_e32 v145, v73, v145
	v_mul_f32_e32 v146, v74, v146
	v_mul_f32_e32 v147, v75, v147
	v_add_f32_e32 v112, 1.0, v112
	v_add_f32_e32 v113, 1.0, v113
	v_add_f32_e32 v114, 1.0, v114
	v_add_f32_e32 v115, 1.0, v115
	v_fma_f32 v144, v112, v144, v128
	v_fma_f32 v145, v113, v145, v129
	v_fma_f32 v146, v114, v146, v130
	v_fma_f32 v147, v115, v147, v131
	v_cvt_pk_bf16_f32 v166, v144, v145
	v_cvt_pk_bf16_f32 v167, v146, v147
	global_store_dwordx2 v[158:159], v[166:167], off offset:1024
	v_mul_f32_e32 v148, v148, v154
	v_mul_f32_e32 v149, v149, v154
	v_mul_f32_e32 v150, v150, v154
	v_mul_f32_e32 v151, v151, v154
	v_mul_f32_e32 v148, v76, v148
	v_mul_f32_e32 v149, v77, v149
	v_mul_f32_e32 v150, v78, v150
	v_mul_f32_e32 v151, v79, v151
	v_add_f32_e32 v116, 1.0, v116
	v_add_f32_e32 v117, 1.0, v117
	v_add_f32_e32 v118, 1.0, v118
	v_add_f32_e32 v119, 1.0, v119
	v_fma_f32 v148, v116, v148, v132
	v_fma_f32 v149, v117, v149, v133
	v_fma_f32 v150, v118, v150, v134
	v_fma_f32 v151, v119, v151, v135
	v_cvt_pk_bf16_f32 v166, v148, v149
	v_cvt_pk_bf16_f32 v167, v150, v151
	global_store_dwordx2 v[158:159], v[166:167], off offset:1536
	s_add_i32 s46, s46, s76
	s_cmp_lt_i32 s46, 0x8000
	s_cbranch_scc0 .Lmn_p18_done
.Lmn_p18_c2:
	s_ashr_i32 s14, s46, 12
	s_mul_i32 s14, s14, 0x6000
	s_add_u32 s14, s3, s14
	s_addc_u32 s15, s10, 0
	s_add_u32 s100, s14, 0x4000
	s_addc_u32 s101, s15, 0
	v_lshl_add_u64 v[162:163], s[100:101], 0, v[0:1]
	global_load_dwordx4 v[104:107], v[162:163], off offset:0
	global_load_dwordx4 v[108:111], v[162:163], off offset:1024
	global_load_dwordx4 v[112:115], v[162:163], off offset:2048
	global_load_dwordx4 v[116:119], v[162:163], off offset:3072
	s_add_u32 s100, s14, 0x3000
	s_addc_u32 s101, s15, 0
	v_lshl_add_u64 v[164:165], s[100:101], 0, v[0:1]
	global_load_dwordx4 v[120:123], v[164:165], off offset:0
	global_load_dwordx4 v[124:127], v[164:165], off offset:1024
	global_load_dwordx4 v[128:131], v[164:165], off offset:2048
	global_load_dwordx4 v[132:135], v[164:165], off offset:3072
	s_lshl_b32 s8, s76, 1
	s_add_i32 s8, s8, s46
	s_min_i32 s8, s8, 0x7fff
	s_lshl_b32 s8, s8, 11
	s_mov_b32 s9, 0
	v_lshl_add_u64 v[156:157], v[6:7], 0, s[8:9]
	global_load_dwordx2 v[88:89], v[156:157], off offset:0
	global_load_dwordx2 v[90:91], v[156:157], off offset:512
	global_load_dwordx2 v[92:93], v[156:157], off offset:1024
	global_load_dwordx2 v[94:95], v[156:157], off offset:1536
	s_waitcnt vmcnt(20)
	v_lshlrev_b32_e32 v136, 16, v96
	v_and_b32_e32 v137, 0xffff0000, v96
	v_lshlrev_b32_e32 v138, 16, v97
	v_and_b32_e32 v139, 0xffff0000, v97
	v_lshlrev_b32_e32 v140, 16, v98
	v_and_b32_e32 v141, 0xffff0000, v98
	v_lshlrev_b32_e32 v142, 16, v99
	v_and_b32_e32 v143, 0xffff0000, v99
	v_lshlrev_b32_e32 v144, 16, v100
	v_and_b32_e32 v145, 0xffff0000, v100
	v_lshlrev_b32_e32 v146, 16, v101
	v_and_b32_e32 v147, 0xffff0000, v101
	v_lshlrev_b32_e32 v148, 16, v102
	v_and_b32_e32 v149, 0xffff0000, v102
	v_lshlrev_b32_e32 v150, 16, v103
	v_and_b32_e32 v151, 0xffff0000, v103
	v_mul_f32_e32 v152, v136, v136
	v_mul_f32_e32 v153, v137, v137
	v_fmac_f32_e32 v152, v138, v138
	v_fmac_f32_e32 v153, v139, v139
	v_fmac_f32_e32 v152, v140, v140
	v_fmac_f32_e32 v153, v141, v141
	v_fmac_f32_e32 v152, v142, v142
	v_fmac_f32_e32 v153, v143, v143
	v_fmac_f32_e32 v152, v144, v144
	v_fmac_f32_e32 v153, v145, v145
	v_fmac_f32_e32 v152, v146, v146
	v_fmac_f32_e32 v153, v147, v147
	v_fmac_f32_e32 v152, v148, v148
	v_fmac_f32_e32 v153, v149, v149
	v_fmac_f32_e32 v152, v150, v150
	v_fmac_f32_e32 v153, v151, v151
	v_add_f32_e32 v152, v152, v153
	ds_bpermute_b32 v153, v8, v152
	s_waitcnt lgkmcnt(0)
; __device__ __forceinline__ unsigned cvt_pk_bf16(float lo, float hi) { unsigned r; asm volatile("v_cvt_pk_bf16_f32 %0, %1, %2" : "=v"(r) : "v"(lo), "v"(hi)); return r; }
;     ...
;         for (int j = 0; j < 4; ++j) ss += (v[j].x * v[j].x + v[j].y * v[j].y) + (v[j].z * v[j].z + v[j].w * v[j].w);
;         const float rstd = rsqrtf(wave_sum(ss) * (1.0f / DM) + EPS);
;         const f32x4* g4 = (const f32x4*)gnorm + f_lane; const f32x4* sh4 = (const f32x4*)(modl + b * MODS + shc * DM) + f_lane; const f32x4* sc4 = (const f32x4*)(modl + b * MODS + scc * DM) + f_lane;
;         u32x2* o8 = (u32x2*)(H + (size_t)row * DM) + f_lane;
; #pragma unroll
;         for (int j = 0; j < 4; ++j) { const f32x4 y = v[j] * rstd * g4[64 * j] * (sc4[64 * j] + 1.0f) + sh4[64 * j];
;             u32x2 w; w.x = cvt_pk_bf16(y.x, y.y); w.y = cvt_pk_bf16(y.z, y.w); o8[64 * j] = w; }
; __device__ __forceinline__ void xcd_barrier(const XcdBarrier& b) {
;     asm volatile("s_waitcnt vmcnt(0)" ::: "memory");
;     __syncthreads();
;     if (threadIdx.x == 0) {
;         unsigned* bar = b.bar;
;         __builtin_amdgcn_s_waitcnt(0);
;         unsigned nloc = b.st[0], nx = b.st[1];
;         if (nloc == 0u) { xcd_barrier_complete(bar, b.x, nloc, nx); b.st[0] = nloc; b.st[1] = nx; }
	v_add_f32_e32 v152, v152, v153
	ds_bpermute_b32 v153, v9, v152
	s_waitcnt lgkmcnt(0)
	v_add_f32_e32 v152, v152, v153
	ds_bpermute_b32 v153, v10, v152
	s_waitcnt lgkmcnt(0)
	v_add_f32_e32 v152, v152, v153
	ds_bpermute_b32 v153, v11, v152
	s_waitcnt lgkmcnt(0)
	v_add_f32_e32 v152, v152, v153
	ds_bpermute_b32 v153, v12, v152
	s_waitcnt lgkmcnt(0)
	v_add_f32_e32 v152, v152, v153
	ds_bpermute_b32 v153, v13, v152
	s_waitcnt lgkmcnt(0)
	v_add_f32_e32 v152, v152, v153
	v_fmamk_f32 v152, v152, 0x3a800000, v14
	v_mul_f32_e32 v153, 0x4b800000, v152
	v_cmp_gt_f32_e32 vcc, 0x800000, v152
	s_nop 1
	v_cndmask_b32_e32 v152, v152, v153, vcc
	v_rsq_f32_e32 v152, v152
	s_nop 0
	v_mul_f32_e32 v153, 0x45800000, v152
	v_cndmask_b32_e32 v154, v152, v153, vcc
	s_waitcnt vmcnt(4)
	s_lshl_b32 s8, s46, 11
	s_mov_b32 s9, 0
	v_lshl_add_u64 v[158:159], v[4:5], 0, s[8:9]
	v_mul_f32_e32 v136, v136, v154
	v_mul_f32_e32 v137, v137, v154
	v_mul_f32_e32 v138, v138, v154
	v_mul_f32_e32 v139, v139, v154
	v_mul_f32_e32 v136, v64, v136
	v_mul_f32_e32 v137, v65, v137
	v_mul_f32_e32 v138, v66, v138
	v_mul_f32_e32 v139, v67, v139
	v_add_f32_e32 v104, 1.0, v104
	v_add_f32_e32 v105, 1.0, v105
	v_add_f32_e32 v106, 1.0, v106
	v_add_f32_e32 v107, 1.0, v107
	v_fma_f32 v136, v104, v136, v120
	v_fma_f32 v137, v105, v137, v121
	v_fma_f32 v138, v106, v138, v122
	v_fma_f32 v139, v107, v139, v123
	v_cvt_pk_bf16_f32 v166, v136, v137
	v_cvt_pk_bf16_f32 v167, v138, v139
	global_store_dwordx2 v[158:159], v[166:167], off offset:0
	v_mul_f32_e32 v140, v140, v154
	v_mul_f32_e32 v141, v141, v154
	v_mul_f32_e32 v142, v142, v154
	v_mul_f32_e32 v143, v143, v154
	v_mul_f32_e32 v140, v68, v140
	v_mul_f32_e32 v141, v69, v141
	v_mul_f32_e32 v142, v70, v142
	v_mul_f32_e32 v143, v71, v143
	v_add_f32_e32 v108, 1.0, v108
	v_add_f32_e32 v109, 1.0, v109
	v_add_f32_e32 v110, 1.0, v110
	v_add_f32_e32 v111, 1.0, v111
	v_fma_f32 v140, v108, v140, v124
	v_fma_f32 v141, v109, v141, v125
	v_fma_f32 v142, v110, v142, v126
	v_fma_f32 v143, v111, v143, v127
	v_cvt_pk_bf16_f32 v166, v140, v141
	v_cvt_pk_bf16_f32 v167, v142, v143
	global_store_dwordx2 v[158:159], v[166:167], off offset:512
	v_mul_f32_e32 v144, v144, v154
	v_mul_f32_e32 v145, v145, v154
	v_mul_f32_e32 v146, v146, v154
	v_mul_f32_e32 v147, v147, v154
	v_mul_f32_e32 v144, v72, v144
	v_mul_f32_e32 v145, v73, v145
	v_mul_f32_e32 v146, v74, v146
	v_mul_f32_e32 v147, v75, v147
	v_add_f32_e32 v112, 1.0, v112
	v_add_f32_e32 v113, 1.0, v113
	v_add_f32_e32 v114, 1.0, v114
	v_add_f32_e32 v115, 1.0, v115
	v_fma_f32 v144, v112, v144, v128
	v_fma_f32 v145, v113, v145, v129
	v_fma_f32 v146, v114, v146, v130
	v_fma_f32 v147, v115, v147, v131
	v_cvt_pk_bf16_f32 v166, v144, v145
	v_cvt_pk_bf16_f32 v167, v146, v147
	global_store_dwordx2 v[158:159], v[166:167], off offset:1024
	v_mul_f32_e32 v148, v148, v154
	v_mul_f32_e32 v149, v149, v154
	v_mul_f32_e32 v150, v150, v154
	v_mul_f32_e32 v151, v151, v154
	v_mul_f32_e32 v148, v76, v148
	v_mul_f32_e32 v149, v77, v149
	v_mul_f32_e32 v150, v78, v150
	v_mul_f32_e32 v151, v79, v151
	v_add_f32_e32 v116, 1.0, v116
	v_add_f32_e32 v117, 1.0, v117
	v_add_f32_e32 v118, 1.0, v118
	v_add_f32_e32 v119, 1.0, v119
	v_fma_f32 v148, v116, v148, v132
	v_fma_f32 v149, v117, v149, v133
	v_fma_f32 v150, v118, v150, v134
	v_fma_f32 v151, v119, v151, v135
	v_cvt_pk_bf16_f32 v166, v148, v149
	v_cvt_pk_bf16_f32 v167, v150, v151
	global_store_dwordx2 v[158:159], v[166:167], off offset:1536
	s_add_i32 s46, s46, s76
	s_cmp_lt_i32 s46, 0x8000
	s_cbranch_scc0 .Lmn_p18_done
	s_branch .Lmn_p18_c0
.Lmn_p18_done:
.LBB0_1746:
	s_mov_b64 s[4:5], s[0:1]
	s_load_dword s3, s[4:5], 0xf8
	s_waitcnt lgkmcnt(0)
	s_cmp_gt_i32 s3, 19
	s_cbranch_scc1 .LBB0_1801
	s_mov_b64 s[4:5], s[0:1]
	s_load_dword s3, s[4:5], 0xfc
	s_waitcnt lgkmcnt(0)
	s_cmp_lt_i32 s3, 20
	s_cbranch_scc1 .LBB0_1801
	s_waitcnt vmcnt(0)
	s_waitcnt vmcnt(0)
	s_barrier
	s_and_saveexec_b64 s[4:5], s[80:81]
	s_cbranch_execz .LBB0_1800
	v_readlane_b32 s6, v251, 0
	v_readlane_b32 s7, v251, 1
	s_add_u32 s6, s6, 0x80200
	s_addc_u32 s7, s7, 0
	s_add_i32 s3, 0, 0x20040
	v_mov_b32_e32 v0, s3
	s_waitcnt vmcnt(0) expcnt(0) lgkmcnt(0)
	ds_read_b32 v2, v0
	s_add_i32 s3, 0, 0x20044
	v_mov_b32_e32 v0, s3
	ds_read_b32 v0, v0
	s_waitcnt lgkmcnt(1)
	v_cmp_ne_u32_e32 vcc, 0, v2
	s_cbranch_vccnz .LBB0_1764
	s_load_dword s8, s[0:1], 0x108
	s_mul_i32 s3, s83, s82
	v_readlane_b32 s40, v251, 0
	v_readlane_b32 s41, v251, 1
	s_mov_b32 s33, 1
	s_waitcnt lgkmcnt(0)
	s_mul_i32 s3, s3, s8
	s_add_u32 s8, s40, 0x80400
	s_addc_u32 s9, s41, 0
	s_add_u32 s10, s40, 0x80500
	s_addc_u32 s11, s41, 0
	s_add_u32 s12, s40, 0x80600
	s_addc_u32 s13, s41, 0
	s_add_u32 s14, s40, 0x80700
	s_addc_u32 s15, s41, 0
	s_add_u32 s16, s40, 0x80800
	s_addc_u32 s17, s41, 0
	s_add_u32 s18, s40, 0x80900
	s_addc_u32 s19, s41, 0
	s_add_u32 s20, s40, 0x80a00
	s_addc_u32 s21, s41, 0
	s_add_u32 s22, s40, 0x80b00
	s_addc_u32 s23, s41, 0
	s_add_u32 s24, s40, 0x80c00
	s_addc_u32 s25, s41, 0
	s_add_u32 s26, s40, 0x80d00
	s_addc_u32 s27, s41, 0
	s_add_u32 s28, s40, 0x80e00
	s_addc_u32 s29, s41, 0
	s_add_u32 s30, s40, 0x80f00
	s_addc_u32 s31, s41, 0
	s_add_u32 s34, s40, 0x81000
	s_addc_u32 s35, s41, 0
	s_add_u32 s36, s40, 0x81100
	s_addc_u32 s37, s41, 0
	s_add_u32 s38, s40, 0x81200
	s_addc_u32 s39, s41, 0
	s_add_u32 s40, s40, 0x81300
	s_addc_u32 s41, s41, 0
	v_mov_b32_e32 v16, 0
	s_branch .LBB0_1752
